# MoE GEMM unit loops (gate/up and down, both layers): per-unit K rotation (start K tile 0/4/8/12 by (pm+pn)&3 with wrap-around) so units sharing operand tiles touch each K slice at different times
# speedup vs baseline: 1.0031x; 1.0031x over previous
.LBB0_1674:
	s_lshl_b32 s45, s12, 6
	s_lshl_b32 s15, s12, 13
	s_lshl_b32 s12, s33, 5
	s_and_b32 s46, s12, 0x60
	s_lshr_b32 s18, s46, 3
	s_add_u32 s12, s34, 0x80000
	v_mov_b32_e32 v1, v135
	v_mov_b32_e32 v2, v136
	s_addc_u32 s13, s35, 0
	s_add_i32 m0, s41, 0x18000
	s_waitcnt vmcnt(2)
	s_barrier
	v_mov_b32_e32 v128, v133
	global_load_lds_dwordx4 v1, s[12:13]
	s_add_i32 m0, s41, 0x1a000
	s_add_i32 s47, s41, 0x8000
	global_load_lds_dwordx4 v2, s[12:13]
	v_mov_b32_e32 v2, v134
	s_mov_b64 s[12:13], 0x80
	v_lshl_add_u64 v[4:5], s[30:31], 0, v[128:129]
	v_mov_b32_e32 v3, v129
	v_lshl_add_u64 v[4:5], v[4:5], 0, s[12:13]
	s_mov_b32 m0, s47
	v_lshl_add_u64 v[2:3], s[30:31], 0, v[2:3]
	s_add_i32 s52, s41, 0xa000
	global_load_lds_dwordx4 v[4:5], off
	v_lshl_add_u64 v[2:3], v[2:3], 0, s[12:13]
	s_mov_b32 m0, s52
	s_add_u32 s20, s34, 0x80800
	global_load_lds_dwordx4 v[2:3], off
	v_mov_b32_e32 v1, v135
	v_mov_b32_e32 v2, v136
	s_addc_u32 s21, s35, 0
	s_add_i32 m0, s41, 0x1c000
	s_sext_i32_i8 s29, s14
	global_load_lds_dwordx4 v1, s[20:21]
	s_add_i32 m0, s41, 0x1e000
	v_ashrrev_i32_e32 v1, 6, v0
	global_load_lds_dwordx4 v2, s[20:21]
	v_and_b32_e32 v2, 48, v0
	v_lshlrev_b32_e32 v4, 6, v0
	s_movk_i32 s14, 0x3c0
	v_lshlrev_b32_e32 v0, 2, v0
	s_cmpk_lt_u32 s90, 0x100
	v_lshl_add_u32 v3, v1, 10, s15
	v_and_or_b32 v2, v4, s14, v2
	v_and_b32_e32 v0, 32, v0
	v_add_lshl_u32 v1, v1, s18, 10
	s_waitcnt vmcnt(6)
	s_cselect_b64 s[14:15], -1, 0
	s_add_u32 s16, s16, 0x62358000
	v_bitop3_b32 v3, v2, v3, v0 bitop3:0xde
	v_bitop3_b32 v137, v2, v1, v0 bitop3:0xde
	s_addc_u32 s17, s17, 0
	s_add_i32 s54, 0, 0x10000
	s_add_i32 s55, 0, 0x14000
	s_mov_b32 s53, 0
	v_add_u32_e32 v138, s54, v137
	v_add_u32_e32 v139, s55, v137
	v_add_u32_e32 v140, 0, v3
	v_mov_b32_e32 v141, 0x7f7f7f7f
	s_mov_b32 s18, 0x3d000000
	s_mov_b64 s[24:25], s[34:35]
	s_mov_b64 s[22:23], s[30:31]
	s_barrier
	s_mov_b32 s99, 0
	s_mov_b32 s100, 0
	s_branch .LBB0_1677

.LBB0_1676:
	s_mov_b32 s99, s100
	s_andn2_b64 vcc, exec, s[26:27]
	s_mov_b32 s28, s20
	s_mov_b32 s29, s63
	s_mov_b64 s[34:35], s[24:25]
	s_mov_b64 s[30:31], s[22:23]
	s_cbranch_vccz .LBB0_1686
.LBB0_1677:
	s_add_i32 s53, s53, 1
	s_mul_i32 s21, s53, s62
	s_add_i32 s21, s21, s92
	s_cmpk_lt_i32 s21, 0x600
	s_cselect_b64 s[26:27], -1, 0
	s_cmpk_gt_i32 s21, 0x5ff
	s_cbranch_scc1 .LBB0_1679
	s_mul_hi_i32 s20, s21, 0x2aaaaaab
	s_lshr_b32 s22, s20, 31
	s_ashr_i32 s20, s20, 4
	s_add_i32 s24, s20, s22
	s_mul_i32 s20, s24, 0x60
	s_sub_i32 s20, s21, s20
	s_mul_i32 s21, s20, 43
	s_bfe_u32 s22, s21, 0x1000f
	s_bfe_u32 s21, s21, 0x80008
	s_add_i32 s36, s21, s22
	s_mul_i32 s22, s36, 6
	s_sub_i32 s20, s20, s22
	s_mul_i32 s21, s24, 6
	s_sext_i32_i8 s20, s20
	s_add_i32 s20, s21, s20
	s_ashr_i32 s21, s20, 31
	s_lshl_b64 s[22:23], s[20:21], 19
	s_add_u32 s22, s19, s22
	s_sext_i32_i8 s63, s36
	s_addc_u32 s23, s38, s23
	s_ashr_i32 s25, s24, 31
	s_bfe_i64 s[36:37], s[36:37], 0x80000
	s_lshl_b64 s[24:25], s[24:25], 23
	s_lshl_b64 s[36:37], s[36:37], 12
	s_add_u32 s21, s39, s24
	s_addc_u32 s25, s40, s25
	s_add_u32 s24, s21, s36
	s_addc_u32 s25, s25, s37
	s_add_i32 s100, s20, s63
	s_and_b32 s100, s100, 3
	s_lshl_b32 s100, s100, 2
	s_lshl_b32 s98, s100, 7
	s_add_u32 s22, s22, s98
	s_addc_u32 s23, s23, 0
	s_lshl_b32 s98, s100, 19
	s_add_u32 s24, s24, s98
	s_addc_u32 s25, s25, 0

.LBB0_1680:
	ds_read_b128 v[142:145], v138
	ds_read_b128 v[146:149], v138 offset:1024
	ds_read_b128 v[150:153], v138 offset:2048
	ds_read_b128 v[154:157], v138 offset:3072
	ds_read_b128 v[158:161], v139
	ds_read_b128 v[162:165], v139 offset:1024
	ds_read_b128 v[166:169], v139 offset:2048
	ds_read_b128 v[170:173], v139 offset:3072
	s_add_u32 s34, s30, 0xfffc0080
	s_addc_u32 s35, s31, -1
	s_cmp_eq_u32 s99, 14
	s_cselect_b32 s98, 0x800, 0
	s_lshl_b32 s101, s98, 12
	s_sub_u32 s34, s34, s98
	s_subb_u32 s35, s35, 0
	s_sub_u32 s36, s21, s101
	s_subb_u32 s37, s48, 0
	s_cmp_eq_u32 s49, 12
	s_cselect_b32 s35, s23, s35
	s_cselect_b32 s34, s22, s34
	s_cselect_b32 s37, s25, s37
	s_cselect_b32 s36, s24, s36
	v_mov_b32_e32 v128, v133
	v_mov_b32_e32 v130, v134
	s_add_i32 m0, s41, 0xc000
	ds_read_b128 v[174:177], v140
	ds_read_b128 v[178:181], v140 offset:1024
	ds_read_b128 v[182:185], v140 offset:2048
	ds_read_b128 v[186:189], v140 offset:3072
	ds_read_b128 v[190:193], v140 offset:4096
	ds_read_b128 v[194:197], v140 offset:5120
	ds_read_b128 v[198:201], v140 offset:6144
	ds_read_b128 v[202:205], v140 offset:7168
	s_nop 0
	global_load_lds_dwordx4 v128, s[30:31]
	s_add_i32 m0, s41, 0xe000
	s_nop 0
	global_load_lds_dwordx4 v130, s[30:31]
	s_waitcnt vmcnt(8)
	s_waitcnt lgkmcnt(0)
	s_barrier
	s_setprio 1
	s_waitcnt lgkmcnt(0)
	v_mfma_scale_f32_16x16x128_f8f6f4 v[124:127], v[142:149], v[174:181], v[124:127], v141, v141 op_sel_hi:[0,0,0]
	v_mfma_scale_f32_16x16x128_f8f6f4 v[116:119], v[150:157], v[174:181], v[116:119], v141, v141 op_sel_hi:[0,0,0]
	v_mfma_scale_f32_16x16x128_f8f6f4 v[108:111], v[142:149], v[182:189], v[108:111], v141, v141 op_sel_hi:[0,0,0]
	v_mfma_scale_f32_16x16x128_f8f6f4 v[100:103], v[150:157], v[182:189], v[100:103], v141, v141 op_sel_hi:[0,0,0]
	v_mfma_scale_f32_16x16x128_f8f6f4 v[206:209], v[142:149], v[190:197], v[92:95], v141, v141 op_sel_hi:[0,0,0]
	v_mfma_scale_f32_16x16x128_f8f6f4 v[210:213], v[150:157], v[190:197], v[84:87], v141, v141 op_sel_hi:[0,0,0]
	v_mfma_scale_f32_16x16x128_f8f6f4 v[214:217], v[142:149], v[198:205], v[76:79], v141, v141 op_sel_hi:[0,0,0]
	v_mfma_scale_f32_16x16x128_f8f6f4 v[218:221], v[150:157], v[198:205], v[68:71], v141, v141 op_sel_hi:[0,0,0]
	s_setprio 0
	s_setprio 1
	v_mfma_scale_f32_16x16x128_f8f6f4 v[120:123], v[158:165], v[174:181], v[120:123], v141, v141 op_sel_hi:[0,0,0]
	v_mfma_scale_f32_16x16x128_f8f6f4 v[112:115], v[166:173], v[174:181], v[112:115], v141, v141 op_sel_hi:[0,0,0]
	v_mfma_scale_f32_16x16x128_f8f6f4 v[104:107], v[158:165], v[182:189], v[104:107], v141, v141 op_sel_hi:[0,0,0]
	v_mfma_scale_f32_16x16x128_f8f6f4 v[96:99], v[166:173], v[182:189], v[96:99], v141, v141 op_sel_hi:[0,0,0]
	v_mfma_scale_f32_16x16x128_f8f6f4 v[174:177], v[158:165], v[190:197], v[88:91], v141, v141 op_sel_hi:[0,0,0]
	v_mfma_scale_f32_16x16x128_f8f6f4 v[178:181], v[166:173], v[190:197], v[80:83], v141, v141 op_sel_hi:[0,0,0]
	v_mfma_scale_f32_16x16x128_f8f6f4 v[182:185], v[158:165], v[198:205], v[72:75], v141, v141 op_sel_hi:[0,0,0]
	v_mfma_scale_f32_16x16x128_f8f6f4 v[186:189], v[166:173], v[198:205], v[64:67], v141, v141 op_sel_hi:[0,0,0]
	s_setprio 0
	s_barrier
	s_add_i32 s64, s54, s3
	v_mov_b32_e32 v128, v135
	v_mov_b32_e32 v130, v136
	s_mov_b32 m0, s64
	s_nop 0
	ds_read_b128 v[64:67], v140 offset:16384
	ds_read_b128 v[68:71], v140 offset:17408
	ds_read_b128 v[72:75], v140 offset:18432
	ds_read_b128 v[76:79], v140 offset:19456
	ds_read_b128 v[80:83], v140 offset:20480
	ds_read_b128 v[84:87], v140 offset:21504
	ds_read_b128 v[88:91], v140 offset:22528
	ds_read_b128 v[92:95], v140 offset:23552
	v_mov_b32_e32 v131, v129
	global_load_lds_dwordx4 v128, s[36:37]
	s_add_i32 m0, s64, 0x2000
	v_mov_b32_e32 v128, v135
	global_load_lds_dwordx4 v130, s[36:37]
	v_mov_b32_e32 v130, v136
	s_add_i32 s64, s55, s3
	v_lshl_add_u64 v[190:191], s[36:37], 0, v[128:129]
	v_lshl_add_u64 v[190:191], v[190:191], 0, s[8:9]
	s_mov_b32 m0, s64
	v_lshl_add_u64 v[130:131], s[36:37], 0, v[130:131]
	global_load_lds_dwordx4 v[190:191], off
	v_lshl_add_u64 v[130:131], v[130:131], 0, s[8:9]
	s_add_i32 m0, s64, 0x2000
	v_mov_b32_e32 v128, v133
	global_load_lds_dwordx4 v[130:131], off
	v_mov_b32_e32 v130, v134
	s_mov_b32 m0, s41
	s_nop 0
	global_load_lds_dwordx4 v128, s[34:35]
	s_mov_b32 m0, s42
	s_nop 0
	global_load_lds_dwordx4 v130, s[34:35]
	s_waitcnt vmcnt(8)
	s_waitcnt lgkmcnt(0)
	s_barrier
	s_setprio 1
	s_waitcnt lgkmcnt(0)
	v_mfma_scale_f32_16x16x128_f8f6f4 v[60:63], v[142:149], v[64:71], v[60:63], v141, v141 op_sel_hi:[0,0,0]
	v_mfma_scale_f32_16x16x128_f8f6f4 v[52:55], v[150:157], v[64:71], v[52:55], v141, v141 op_sel_hi:[0,0,0]
	v_mfma_scale_f32_16x16x128_f8f6f4 v[44:47], v[142:149], v[72:79], v[44:47], v141, v141 op_sel_hi:[0,0,0]
	v_mfma_scale_f32_16x16x128_f8f6f4 v[198:201], v[150:157], v[72:79], v[36:39], v141, v141 op_sel_hi:[0,0,0]
	v_mfma_scale_f32_16x16x128_f8f6f4 v[202:205], v[142:149], v[80:87], v[28:31], v141, v141 op_sel_hi:[0,0,0]
	v_mfma_scale_f32_16x16x128_f8f6f4 v[222:225], v[150:157], v[80:87], v[20:23], v141, v141 op_sel_hi:[0,0,0]
	v_mfma_scale_f32_16x16x128_f8f6f4 v[226:229], v[142:149], v[88:95], v[12:15], v141, v141 op_sel_hi:[0,0,0]
	v_mfma_scale_f32_16x16x128_f8f6f4 v[230:233], v[150:157], v[88:95], v[4:7], v141, v141 op_sel_hi:[0,0,0]
	s_setprio 0
	s_setprio 1
	v_mfma_scale_f32_16x16x128_f8f6f4 v[56:59], v[158:165], v[64:71], v[56:59], v141, v141 op_sel_hi:[0,0,0]
	v_mfma_scale_f32_16x16x128_f8f6f4 v[48:51], v[166:173], v[64:71], v[48:51], v141, v141 op_sel_hi:[0,0,0]
	v_mfma_scale_f32_16x16x128_f8f6f4 v[40:43], v[158:165], v[72:79], v[40:43], v141, v141 op_sel_hi:[0,0,0]
	v_mfma_scale_f32_16x16x128_f8f6f4 v[234:237], v[166:173], v[72:79], v[32:35], v141, v141 op_sel_hi:[0,0,0]
	v_mfma_scale_f32_16x16x128_f8f6f4 v[238:241], v[158:165], v[80:87], v[24:27], v141, v141 op_sel_hi:[0,0,0]
	v_mfma_scale_f32_16x16x128_f8f6f4 v[242:245], v[166:173], v[80:87], v[16:19], v141, v141 op_sel_hi:[0,0,0]
	v_mfma_scale_f32_16x16x128_f8f6f4 v[246:249], v[158:165], v[88:95], v[8:11], v141, v141 op_sel_hi:[0,0,0]
	v_mfma_scale_f32_16x16x128_f8f6f4 v[250:253], v[166:173], v[88:95], v[0:3], v141, v141 op_sel_hi:[0,0,0]
	s_setprio 0
	s_barrier
	s_add_i32 s66, 0, 0x18000
	s_nop 2
	v_add_u32_e32 v8, s66, v137
	s_add_i32 s67, 0, 0x1c000
	ds_read_b128 v[0:3], v8
	ds_read_b128 v[4:7], v8 offset:1024
	ds_read_b128 v[142:145], v8 offset:2048
	ds_read_b128 v[146:149], v8 offset:3072
	v_add_u32_e32 v8, s67, v137
	ds_read_b128 v[150:153], v8
	ds_read_b128 v[154:157], v8 offset:1024
	ds_read_b128 v[158:161], v8 offset:2048
	ds_read_b128 v[162:165], v8 offset:3072
	s_add_u32 s64, s34, 0x40000
	v_mov_b32_e32 v64, v133
	v_mov_b32_e32 v65, v134
	s_addc_u32 s65, s35, 0
	s_mov_b32 m0, s43
	ds_read_b128 v[8:11], v140 offset:32768
	ds_read_b128 v[12:15], v140 offset:33792
	ds_read_b128 v[16:19], v140 offset:34816
	ds_read_b128 v[20:23], v140 offset:35840
	ds_read_b128 v[24:27], v140 offset:36864
	ds_read_b128 v[28:31], v140 offset:37888
	ds_read_b128 v[32:35], v140 offset:38912
	ds_read_b128 v[36:39], v140 offset:39936
	s_nop 0
	global_load_lds_dwordx4 v64, s[64:65]
	s_mov_b32 m0, s44
	s_nop 0
	global_load_lds_dwordx4 v65, s[64:65]
	s_waitcnt vmcnt(8)
	s_waitcnt lgkmcnt(0)
	s_barrier
	s_setprio 1
	s_waitcnt lgkmcnt(0)
	v_mfma_scale_f32_16x16x128_f8f6f4 v[124:127], v[0:7], v[8:15], v[124:127], v141, v141 op_sel_hi:[0,0,0]
	v_mfma_scale_f32_16x16x128_f8f6f4 v[116:119], v[142:149], v[8:15], v[116:119], v141, v141 op_sel_hi:[0,0,0]
	v_mfma_scale_f32_16x16x128_f8f6f4 v[108:111], v[0:7], v[16:23], v[108:111], v141, v141 op_sel_hi:[0,0,0]
	v_mfma_scale_f32_16x16x128_f8f6f4 v[100:103], v[142:149], v[16:23], v[100:103], v141, v141 op_sel_hi:[0,0,0]
	v_mfma_scale_f32_16x16x128_f8f6f4 v[92:95], v[0:7], v[24:31], v[206:209], v141, v141 op_sel_hi:[0,0,0]
	v_mfma_scale_f32_16x16x128_f8f6f4 v[84:87], v[142:149], v[24:31], v[210:213], v141, v141 op_sel_hi:[0,0,0]
	v_mfma_scale_f32_16x16x128_f8f6f4 v[76:79], v[0:7], v[32:39], v[214:217], v141, v141 op_sel_hi:[0,0,0]
	v_mfma_scale_f32_16x16x128_f8f6f4 v[68:71], v[142:149], v[32:39], v[218:221], v141, v141 op_sel_hi:[0,0,0]
	s_setprio 0
	s_setprio 1
	v_mfma_scale_f32_16x16x128_f8f6f4 v[120:123], v[150:157], v[8:15], v[120:123], v141, v141 op_sel_hi:[0,0,0]
	v_mfma_scale_f32_16x16x128_f8f6f4 v[112:115], v[158:165], v[8:15], v[112:115], v141, v141 op_sel_hi:[0,0,0]
	v_mfma_scale_f32_16x16x128_f8f6f4 v[104:107], v[150:157], v[16:23], v[104:107], v141, v141 op_sel_hi:[0,0,0]
	v_mfma_scale_f32_16x16x128_f8f6f4 v[96:99], v[158:165], v[16:23], v[96:99], v141, v141 op_sel_hi:[0,0,0]
	v_mfma_scale_f32_16x16x128_f8f6f4 v[88:91], v[150:157], v[24:31], v[174:177], v141, v141 op_sel_hi:[0,0,0]
	v_mfma_scale_f32_16x16x128_f8f6f4 v[80:83], v[158:165], v[24:31], v[178:181], v141, v141 op_sel_hi:[0,0,0]
	v_mfma_scale_f32_16x16x128_f8f6f4 v[72:75], v[150:157], v[32:39], v[182:185], v141, v141 op_sel_hi:[0,0,0]
	v_mfma_scale_f32_16x16x128_f8f6f4 v[64:67], v[158:165], v[32:39], v[186:189], v141, v141 op_sel_hi:[0,0,0]
	s_setprio 0
	s_barrier
	s_add_u32 s64, s36, 0x80000
	s_addc_u32 s65, s37, 0
	s_add_i32 s66, s66, s3
	v_mov_b32_e32 v8, v135
	v_mov_b32_e32 v9, v136
	s_mov_b32 m0, s66
	ds_read_b128 v[166:169], v140 offset:49152
	ds_read_b128 v[170:173], v140 offset:50176
	ds_read_b128 v[174:177], v140 offset:51200
	ds_read_b128 v[178:181], v140 offset:52224
	ds_read_b128 v[182:185], v140 offset:53248
	ds_read_b128 v[186:189], v140 offset:54272
	ds_read_b128 v[190:193], v140 offset:55296
	ds_read_b128 v[194:197], v140 offset:56320
	v_mov_b32_e32 v128, v133
	global_load_lds_dwordx4 v8, s[64:65]
	s_add_i32 m0, s66, 0x2000
	s_add_u32 s36, s36, 0x80800
	global_load_lds_dwordx4 v9, s[64:65]
	v_mov_b32_e32 v8, v135
	v_mov_b32_e32 v9, v136
	s_addc_u32 s37, s37, 0
	s_add_i32 s64, s67, s3
	s_mov_b32 m0, s64
	s_nop 0
	global_load_lds_dwordx4 v8, s[36:37]
	s_add_i32 m0, s64, 0x2000
	v_mov_b32_e32 v8, v134
	global_load_lds_dwordx4 v9, s[36:37]
	v_mov_b32_e32 v9, v129
	v_lshl_add_u64 v[10:11], s[34:35], 0, v[128:129]
	v_lshl_add_u64 v[10:11], v[10:11], 0, s[12:13]
	s_mov_b32 m0, s47
	v_lshl_add_u64 v[8:9], s[34:35], 0, v[8:9]
	global_load_lds_dwordx4 v[10:11], off
	v_lshl_add_u64 v[8:9], v[8:9], 0, s[12:13]
	s_mov_b32 m0, s52
	s_nop 0
	global_load_lds_dwordx4 v[8:9], off
	s_waitcnt vmcnt(8)
	s_waitcnt lgkmcnt(0)
	s_barrier
	s_setprio 1
	s_waitcnt lgkmcnt(0)
	v_mfma_scale_f32_16x16x128_f8f6f4 v[60:63], v[0:7], v[166:173], v[60:63], v141, v141 op_sel_hi:[0,0,0]
	v_mfma_scale_f32_16x16x128_f8f6f4 v[52:55], v[142:149], v[166:173], v[52:55], v141, v141 op_sel_hi:[0,0,0]
	v_mfma_scale_f32_16x16x128_f8f6f4 v[44:47], v[0:7], v[174:181], v[44:47], v141, v141 op_sel_hi:[0,0,0]
	v_mfma_scale_f32_16x16x128_f8f6f4 v[36:39], v[142:149], v[174:181], v[198:201], v141, v141 op_sel_hi:[0,0,0]
	v_mfma_scale_f32_16x16x128_f8f6f4 v[28:31], v[0:7], v[182:189], v[202:205], v141, v141 op_sel_hi:[0,0,0]
	v_mfma_scale_f32_16x16x128_f8f6f4 v[20:23], v[142:149], v[182:189], v[222:225], v141, v141 op_sel_hi:[0,0,0]
	v_mfma_scale_f32_16x16x128_f8f6f4 v[12:15], v[0:7], v[190:197], v[226:229], v141, v141 op_sel_hi:[0,0,0]
	v_mfma_scale_f32_16x16x128_f8f6f4 v[4:7], v[142:149], v[190:197], v[230:233], v141, v141 op_sel_hi:[0,0,0]
	s_setprio 0
	s_setprio 1
	v_mfma_scale_f32_16x16x128_f8f6f4 v[56:59], v[150:157], v[166:173], v[56:59], v141, v141 op_sel_hi:[0,0,0]
	v_mfma_scale_f32_16x16x128_f8f6f4 v[48:51], v[158:165], v[166:173], v[48:51], v141, v141 op_sel_hi:[0,0,0]
	v_mfma_scale_f32_16x16x128_f8f6f4 v[40:43], v[150:157], v[174:181], v[40:43], v141, v141 op_sel_hi:[0,0,0]
	v_mfma_scale_f32_16x16x128_f8f6f4 v[32:35], v[158:165], v[174:181], v[234:237], v141, v141 op_sel_hi:[0,0,0]
	v_mfma_scale_f32_16x16x128_f8f6f4 v[24:27], v[150:157], v[182:189], v[238:241], v141, v141 op_sel_hi:[0,0,0]
	v_mfma_scale_f32_16x16x128_f8f6f4 v[16:19], v[158:165], v[182:189], v[242:245], v141, v141 op_sel_hi:[0,0,0]
	v_mfma_scale_f32_16x16x128_f8f6f4 v[8:11], v[150:157], v[190:197], v[246:249], v141, v141 op_sel_hi:[0,0,0]
	v_mfma_scale_f32_16x16x128_f8f6f4 v[0:3], v[158:165], v[190:197], v[250:253], v141, v141 op_sel_hi:[0,0,0]
	s_setprio 0
	s_barrier
	s_add_i32 s49, s49, 2
	s_add_u32 s21, s21, 0x100000
	s_addc_u32 s48, s48, 0
	s_add_u32 s30, s30, 0x100
	s_addc_u32 s31, s31, 0
	s_sub_u32 s21, s21, s101
	s_subb_u32 s48, s48, 0
	s_sub_u32 s30, s30, s98
	s_subb_u32 s31, s31, 0
	s_add_i32 s99, s99, 2
	s_and_b32 s99, s99, 15
	s_cmp_gt_u32 s49, 13
	s_cbranch_scc0 .LBB0_1680
	s_and_b64 vcc, exec, s[14:15]
	s_cbranch_vccz .LBB0_1683
	s_barrier

.LBB0_1745:
	s_lshl_b32 s44, s12, 6
	s_lshl_b32 s15, s12, 13
	s_lshl_b32 s12, s33, 5
	s_and_b32 s45, s12, 0x60
	s_lshr_b32 s20, s45, 3
	v_mov_b32_e32 v1, v138
	v_mov_b32_e32 v2, v137
	s_add_u32 s12, s30, 0x40000
	s_waitcnt vmcnt(2)
	s_barrier
	s_addc_u32 s13, s31, 0
	s_add_i32 m0, s40, 0x18000
	v_mov_b32_e32 v128, v135
	global_load_lds_dwordx4 v2, s[12:13]
	s_add_i32 m0, s40, 0x1a000
	v_mov_b32_e32 v2, v136
	global_load_lds_dwordx4 v1, s[12:13]
	s_mov_b64 s[12:13], 0x80
	v_lshl_add_u64 v[4:5], s[28:29], 0, v[128:129]
	s_add_i32 s46, s40, 0x8000
	v_mov_b32_e32 v3, v129
	v_lshl_add_u64 v[4:5], v[4:5], 0, s[12:13]
	s_mov_b32 m0, s46
	v_lshl_add_u64 v[2:3], s[28:29], 0, v[2:3]
	s_add_i32 s47, s40, 0xa000
	global_load_lds_dwordx4 v[4:5], off
	v_lshl_add_u64 v[2:3], v[2:3], 0, s[12:13]
	s_mov_b32 m0, s47
	s_add_u32 s18, s30, 0x40800
	global_load_lds_dwordx4 v[2:3], off
	v_mov_b32_e32 v1, v138
	v_mov_b32_e32 v2, v137
	s_addc_u32 s19, s31, 0
	s_add_i32 m0, s40, 0x1c000
	s_sext_i32_i8 s27, s14
	global_load_lds_dwordx4 v2, s[18:19]
	s_add_i32 m0, s40, 0x1e000
	v_and_b32_e32 v2, 48, v0
	global_load_lds_dwordx4 v1, s[18:19]
	v_ashrrev_i32_e32 v1, 6, v0
	v_lshlrev_b32_e32 v4, 6, v0
	s_movk_i32 s14, 0x3c0
	v_lshlrev_b32_e32 v0, 2, v0
	s_cmpk_lt_u32 s90, 0x100
	v_lshl_add_u32 v3, v1, 10, s15
	v_and_or_b32 v2, v4, s14, v2
	v_and_b32_e32 v0, 32, v0
	v_add_lshl_u32 v1, v1, s20, 10
	s_waitcnt vmcnt(6)
	s_cselect_b64 s[14:15], -1, 0
	s_add_u32 s16, s16, 0x68358000
	v_bitop3_b32 v3, v2, v3, v0 bitop3:0xde
	v_bitop3_b32 v139, v2, v1, v0 bitop3:0xde
	s_addc_u32 s17, s17, 0
	s_add_i32 s53, 0, 0x10000
	s_add_i32 s54, 0, 0x14000
	s_mov_b32 s52, 0
	v_add_u32_e32 v140, s53, v139
	v_add_u32_e32 v141, s54, v139
	v_add_u32_e32 v142, 0, v3
	v_mov_b32_e32 v143, 0x7f7f7f7f
	s_mov_b64 s[22:23], s[30:31]
	s_mov_b64 s[20:21], s[28:29]
	s_barrier
	s_mov_b32 s99, 0
	s_mov_b32 s100, 0
	s_branch .LBB0_1748

.LBB0_1747:
	s_mov_b32 s99, s100
	s_andn2_b64 vcc, exec, s[24:25]
	s_mov_b32 s26, s18
	s_mov_b32 s27, s55
	s_mov_b64 s[30:31], s[22:23]
	s_mov_b64 s[28:29], s[20:21]
	s_cbranch_vccz .LBB0_1757
.LBB0_1748:
	s_add_i32 s52, s52, 1
	s_mul_i32 s19, s52, s62
	s_add_i32 s19, s19, s92
	s_cmpk_lt_i32 s19, 0x300
	s_cselect_b64 s[24:25], -1, 0
	s_cmpk_gt_i32 s19, 0x2ff
	s_cbranch_scc1 .LBB0_1750
	s_mul_hi_i32 s18, s19, 0x2aaaaaab
	s_lshr_b32 s20, s18, 31
	s_ashr_i32 s18, s18, 3
	s_add_i32 s22, s18, s20
	s_mul_i32 s18, s22, 48
	s_sub_i32 s18, s19, s18
	s_mul_i32 s19, s18, 43
	s_bfe_u32 s20, s19, 0x1000f
	s_bfe_u32 s19, s19, 0x80008
	s_add_i32 s34, s19, s20
	s_mul_i32 s20, s34, 6
	s_sub_i32 s18, s18, s20
	s_mul_i32 s19, s22, 6
	s_sext_i32_i8 s18, s18
	s_add_i32 s18, s19, s18
	s_ashr_i32 s19, s18, 31
	s_lshl_b64 s[20:21], s[18:19], 19
	s_add_u32 s20, s36, s20
	s_sext_i32_i8 s55, s34
	s_addc_u32 s21, s37, s21
	s_ashr_i32 s23, s22, 31
	s_bfe_i64 s[34:35], s[34:35], 0x80000
	s_lshl_b64 s[22:23], s[22:23], 22
	s_lshl_b64 s[34:35], s[34:35], 12
	s_add_u32 s19, s38, s22
	s_addc_u32 s23, s39, s23
	s_add_u32 s22, s19, s34
	s_addc_u32 s23, s23, s35
	s_add_i32 s100, s18, s55
	s_and_b32 s100, s100, 3
	s_lshl_b32 s100, s100, 2
	s_lshl_b32 s98, s100, 7
	s_add_u32 s20, s20, s98
	s_addc_u32 s21, s21, 0
	s_lshl_b32 s98, s100, 18
	s_add_u32 s22, s22, s98
	s_addc_u32 s23, s23, 0

.LBB0_1751:
	ds_read_b128 v[144:147], v140
	ds_read_b128 v[148:151], v140 offset:1024
	ds_read_b128 v[152:155], v140 offset:2048
	ds_read_b128 v[156:159], v140 offset:3072
	ds_read_b128 v[160:163], v141
	ds_read_b128 v[164:167], v141 offset:1024
	ds_read_b128 v[168:171], v141 offset:2048
	ds_read_b128 v[172:175], v141 offset:3072
	s_add_u32 s30, s28, 0xfffc0080
	s_addc_u32 s31, s29, -1
	s_cmp_eq_u32 s99, 14
	s_cselect_b32 s98, 0x800, 0
	s_lshl_b32 s101, s98, 11
	s_sub_u32 s30, s30, s98
	s_subb_u32 s31, s31, 0
	s_sub_u32 s34, s19, s101
	s_subb_u32 s35, s48, 0
	s_cmp_eq_u32 s49, 12
	s_cselect_b32 s31, s21, s31
	s_cselect_b32 s30, s20, s30
	s_cselect_b32 s35, s23, s35
	s_cselect_b32 s34, s22, s34
	v_mov_b32_e32 v128, v136
	v_mov_b32_e32 v130, v135
	s_add_i32 m0, s40, 0xc000
	ds_read_b128 v[176:179], v142
	ds_read_b128 v[180:183], v142 offset:1024
	ds_read_b128 v[184:187], v142 offset:2048
	ds_read_b128 v[188:191], v142 offset:3072
	ds_read_b128 v[192:195], v142 offset:4096
	ds_read_b128 v[196:199], v142 offset:5120
	ds_read_b128 v[200:203], v142 offset:6144
	ds_read_b128 v[204:207], v142 offset:7168
	s_nop 0
	global_load_lds_dwordx4 v130, s[28:29]
	s_add_i32 m0, s40, 0xe000
	s_nop 0
	global_load_lds_dwordx4 v128, s[28:29]
	s_waitcnt vmcnt(8)
	s_waitcnt lgkmcnt(0)
	s_barrier
	s_setprio 1
	s_waitcnt lgkmcnt(0)
	v_mfma_scale_f32_16x16x128_f8f6f4 v[124:127], v[144:151], v[176:183], v[124:127], v143, v143 op_sel_hi:[0,0,0]
	v_mfma_scale_f32_16x16x128_f8f6f4 v[120:123], v[152:159], v[176:183], v[120:123], v143, v143 op_sel_hi:[0,0,0]
	v_mfma_scale_f32_16x16x128_f8f6f4 v[112:115], v[144:151], v[184:191], v[112:115], v143, v143 op_sel_hi:[0,0,0]
	v_mfma_scale_f32_16x16x128_f8f6f4 v[104:107], v[152:159], v[184:191], v[104:107], v143, v143 op_sel_hi:[0,0,0]
	v_mfma_scale_f32_16x16x128_f8f6f4 v[96:99], v[144:151], v[192:199], v[96:99], v143, v143 op_sel_hi:[0,0,0]
	v_mfma_scale_f32_16x16x128_f8f6f4 v[130:133], v[152:159], v[192:199], v[88:91], v143, v143 op_sel_hi:[0,0,0]
	v_mfma_scale_f32_16x16x128_f8f6f4 v[208:211], v[144:151], v[200:207], v[80:83], v143, v143 op_sel_hi:[0,0,0]
	v_mfma_scale_f32_16x16x128_f8f6f4 v[212:215], v[152:159], v[200:207], v[72:75], v143, v143 op_sel_hi:[0,0,0]
	s_setprio 0
	s_setprio 1
	v_mfma_scale_f32_16x16x128_f8f6f4 v[116:119], v[160:167], v[176:183], v[116:119], v143, v143 op_sel_hi:[0,0,0]
	v_mfma_scale_f32_16x16x128_f8f6f4 v[108:111], v[168:175], v[176:183], v[108:111], v143, v143 op_sel_hi:[0,0,0]
	v_mfma_scale_f32_16x16x128_f8f6f4 v[100:103], v[160:167], v[184:191], v[100:103], v143, v143 op_sel_hi:[0,0,0]
	v_mfma_scale_f32_16x16x128_f8f6f4 v[176:179], v[168:175], v[184:191], v[92:95], v143, v143 op_sel_hi:[0,0,0]
	v_mfma_scale_f32_16x16x128_f8f6f4 v[180:183], v[160:167], v[192:199], v[84:87], v143, v143 op_sel_hi:[0,0,0]
	v_mfma_scale_f32_16x16x128_f8f6f4 v[184:187], v[168:175], v[192:199], v[76:79], v143, v143 op_sel_hi:[0,0,0]
	v_mfma_scale_f32_16x16x128_f8f6f4 v[188:191], v[160:167], v[200:207], v[68:71], v143, v143 op_sel_hi:[0,0,0]
	v_mfma_scale_f32_16x16x128_f8f6f4 v[192:195], v[168:175], v[200:207], v[64:67], v143, v143 op_sel_hi:[0,0,0]
	s_setprio 0
	s_barrier
	s_add_i32 s63, s53, s3
	v_mov_b32_e32 v128, v138
	v_mov_b32_e32 v196, v137
	s_mov_b32 m0, s63
	s_nop 0
	ds_read_b128 v[64:67], v142 offset:16384
	ds_read_b128 v[68:71], v142 offset:17408
	ds_read_b128 v[72:75], v142 offset:18432
	ds_read_b128 v[76:79], v142 offset:19456
	ds_read_b128 v[80:83], v142 offset:20480
	ds_read_b128 v[84:87], v142 offset:21504
	ds_read_b128 v[88:91], v142 offset:22528
	ds_read_b128 v[92:95], v142 offset:23552
	v_mov_b32_e32 v197, v129
	global_load_lds_dwordx4 v196, s[34:35]
	s_add_i32 m0, s63, 0x2000
	v_mov_b32_e32 v196, v138
	global_load_lds_dwordx4 v128, s[34:35]
	v_mov_b32_e32 v128, v137
	s_add_i32 s63, s54, s3
	v_lshl_add_u64 v[198:199], s[34:35], 0, v[128:129]
	v_lshl_add_u64 v[198:199], v[198:199], 0, s[8:9]
	s_mov_b32 m0, s63
	v_lshl_add_u64 v[196:197], s[34:35], 0, v[196:197]
	global_load_lds_dwordx4 v[198:199], off
	v_lshl_add_u64 v[196:197], v[196:197], 0, s[8:9]
	s_add_i32 m0, s63, 0x2000
	v_mov_b32_e32 v128, v136
	global_load_lds_dwordx4 v[196:197], off
	v_mov_b32_e32 v196, v135
	s_mov_b32 m0, s40
	s_nop 0
	global_load_lds_dwordx4 v196, s[30:31]
	s_mov_b32 m0, s41
	s_nop 0
	global_load_lds_dwordx4 v128, s[30:31]
	s_waitcnt vmcnt(8)
	s_waitcnt lgkmcnt(0)
	s_barrier
	s_setprio 1
	s_waitcnt lgkmcnt(0)
	v_mfma_scale_f32_16x16x128_f8f6f4 v[60:63], v[144:151], v[64:71], v[60:63], v143, v143 op_sel_hi:[0,0,0]
	v_mfma_scale_f32_16x16x128_f8f6f4 v[56:59], v[152:159], v[64:71], v[56:59], v143, v143 op_sel_hi:[0,0,0]
	v_mfma_scale_f32_16x16x128_f8f6f4 v[48:51], v[144:151], v[72:79], v[48:51], v143, v143 op_sel_hi:[0,0,0]
	v_mfma_scale_f32_16x16x128_f8f6f4 v[196:199], v[152:159], v[72:79], v[40:43], v143, v143 op_sel_hi:[0,0,0]
	v_mfma_scale_f32_16x16x128_f8f6f4 v[200:203], v[144:151], v[80:87], v[32:35], v143, v143 op_sel_hi:[0,0,0]
	v_mfma_scale_f32_16x16x128_f8f6f4 v[204:207], v[152:159], v[80:87], v[24:27], v143, v143 op_sel_hi:[0,0,0]
	v_mfma_scale_f32_16x16x128_f8f6f4 v[216:219], v[144:151], v[88:95], v[16:19], v143, v143 op_sel_hi:[0,0,0]
	v_mfma_scale_f32_16x16x128_f8f6f4 v[220:223], v[152:159], v[88:95], v[8:11], v143, v143 op_sel_hi:[0,0,0]
	s_setprio 0
	s_setprio 1
	v_mfma_scale_f32_16x16x128_f8f6f4 v[52:55], v[160:167], v[64:71], v[52:55], v143, v143 op_sel_hi:[0,0,0]
	v_mfma_scale_f32_16x16x128_f8f6f4 v[224:227], v[168:175], v[64:71], v[44:47], v143, v143 op_sel_hi:[0,0,0]
	v_mfma_scale_f32_16x16x128_f8f6f4 v[228:231], v[160:167], v[72:79], v[36:39], v143, v143 op_sel_hi:[0,0,0]
	v_mfma_scale_f32_16x16x128_f8f6f4 v[232:235], v[168:175], v[72:79], v[28:31], v143, v143 op_sel_hi:[0,0,0]
	v_mfma_scale_f32_16x16x128_f8f6f4 v[236:239], v[160:167], v[80:87], v[20:23], v143, v143 op_sel_hi:[0,0,0]
	v_mfma_scale_f32_16x16x128_f8f6f4 v[240:243], v[168:175], v[80:87], v[12:15], v143, v143 op_sel_hi:[0,0,0]
	v_mfma_scale_f32_16x16x128_f8f6f4 v[244:247], v[160:167], v[88:95], v[4:7], v143, v143 op_sel_hi:[0,0,0]
	v_mfma_scale_f32_16x16x128_f8f6f4 v[248:251], v[168:175], v[88:95], v[0:3], v143, v143 op_sel_hi:[0,0,0]
	s_setprio 0
	s_barrier
	s_add_i32 s63, 0, 0x18000
	s_add_i32 s66, 0, 0x1c000
	s_nop 0
	v_add_u32_e32 v12, s63, v139
	v_add_u32_e32 v16, s66, v139
	ds_read_b128 v[0:3], v12
	ds_read_b128 v[4:7], v12 offset:1024
	ds_read_b128 v[8:11], v12 offset:2048
	ds_read_b128 v[12:15], v12 offset:3072
	ds_read_b128 v[144:147], v16
	ds_read_b128 v[148:151], v16 offset:1024
	ds_read_b128 v[152:155], v16 offset:2048
	ds_read_b128 v[156:159], v16 offset:3072
	s_add_u32 s64, s30, 0x40000
	v_mov_b32_e32 v64, v136
	v_mov_b32_e32 v65, v135
	s_addc_u32 s65, s31, 0
	s_mov_b32 m0, s42
	ds_read_b128 v[16:19], v142 offset:32768
	ds_read_b128 v[20:23], v142 offset:33792
	ds_read_b128 v[24:27], v142 offset:34816
	ds_read_b128 v[28:31], v142 offset:35840
	ds_read_b128 v[32:35], v142 offset:36864
	ds_read_b128 v[36:39], v142 offset:37888
	ds_read_b128 v[40:43], v142 offset:38912
	ds_read_b128 v[44:47], v142 offset:39936
	s_nop 0
	global_load_lds_dwordx4 v65, s[64:65]
	s_mov_b32 m0, s43
	s_nop 0
	global_load_lds_dwordx4 v64, s[64:65]
	s_waitcnt vmcnt(8)
	s_waitcnt lgkmcnt(0)
	s_barrier
	s_setprio 1
	s_waitcnt lgkmcnt(0)
	v_mfma_scale_f32_16x16x128_f8f6f4 v[124:127], v[0:7], v[16:23], v[124:127], v143, v143 op_sel_hi:[0,0,0]
	v_mfma_scale_f32_16x16x128_f8f6f4 v[120:123], v[8:15], v[16:23], v[120:123], v143, v143 op_sel_hi:[0,0,0]
	v_mfma_scale_f32_16x16x128_f8f6f4 v[112:115], v[0:7], v[24:31], v[112:115], v143, v143 op_sel_hi:[0,0,0]
	v_mfma_scale_f32_16x16x128_f8f6f4 v[104:107], v[8:15], v[24:31], v[104:107], v143, v143 op_sel_hi:[0,0,0]
	v_mfma_scale_f32_16x16x128_f8f6f4 v[96:99], v[0:7], v[32:39], v[96:99], v143, v143 op_sel_hi:[0,0,0]
	v_mfma_scale_f32_16x16x128_f8f6f4 v[88:91], v[8:15], v[32:39], v[130:133], v143, v143 op_sel_hi:[0,0,0]
	v_mfma_scale_f32_16x16x128_f8f6f4 v[80:83], v[0:7], v[40:47], v[208:211], v143, v143 op_sel_hi:[0,0,0]
	v_mfma_scale_f32_16x16x128_f8f6f4 v[72:75], v[8:15], v[40:47], v[212:215], v143, v143 op_sel_hi:[0,0,0]
	s_setprio 0
	s_setprio 1
	v_mfma_scale_f32_16x16x128_f8f6f4 v[116:119], v[144:151], v[16:23], v[116:119], v143, v143 op_sel_hi:[0,0,0]
	v_mfma_scale_f32_16x16x128_f8f6f4 v[108:111], v[152:159], v[16:23], v[108:111], v143, v143 op_sel_hi:[0,0,0]
	v_mfma_scale_f32_16x16x128_f8f6f4 v[100:103], v[144:151], v[24:31], v[100:103], v143, v143 op_sel_hi:[0,0,0]
	v_mfma_scale_f32_16x16x128_f8f6f4 v[92:95], v[152:159], v[24:31], v[176:179], v143, v143 op_sel_hi:[0,0,0]
	v_mfma_scale_f32_16x16x128_f8f6f4 v[84:87], v[144:151], v[32:39], v[180:183], v143, v143 op_sel_hi:[0,0,0]
	v_mfma_scale_f32_16x16x128_f8f6f4 v[76:79], v[152:159], v[32:39], v[184:187], v143, v143 op_sel_hi:[0,0,0]
	v_mfma_scale_f32_16x16x128_f8f6f4 v[68:71], v[144:151], v[40:47], v[188:191], v143, v143 op_sel_hi:[0,0,0]
	v_mfma_scale_f32_16x16x128_f8f6f4 v[64:67], v[152:159], v[40:47], v[192:195], v143, v143 op_sel_hi:[0,0,0]
	s_setprio 0
	s_barrier
	s_add_u32 s64, s34, 0x40000
	s_addc_u32 s65, s35, 0
	s_add_i32 s63, s63, s3
	v_mov_b32_e32 v16, v138
	v_mov_b32_e32 v17, v137
	s_mov_b32 m0, s63
	ds_read_b128 v[160:163], v142 offset:49152
	ds_read_b128 v[164:167], v142 offset:50176
	ds_read_b128 v[168:171], v142 offset:51200
	ds_read_b128 v[172:175], v142 offset:52224
	ds_read_b128 v[176:179], v142 offset:53248
	ds_read_b128 v[180:183], v142 offset:54272
	ds_read_b128 v[184:187], v142 offset:55296
	ds_read_b128 v[188:191], v142 offset:56320
	v_mov_b32_e32 v128, v135
	global_load_lds_dwordx4 v17, s[64:65]
	s_add_i32 m0, s63, 0x2000
	s_add_u32 s34, s34, 0x40800
	s_addc_u32 s35, s35, 0
	s_add_i32 s63, s66, s3
	global_load_lds_dwordx4 v16, s[64:65]
	v_mov_b32_e32 v16, v138
	v_mov_b32_e32 v17, v137
	s_mov_b32 m0, s63
	s_nop 0
	global_load_lds_dwordx4 v17, s[34:35]
	s_add_i32 m0, s63, 0x2000
	v_mov_b32_e32 v17, v129
	global_load_lds_dwordx4 v16, s[34:35]
	v_mov_b32_e32 v16, v136
	s_mov_b32 m0, s46
	v_lshl_add_u64 v[18:19], s[30:31], 0, v[128:129]
	v_lshl_add_u64 v[18:19], v[18:19], 0, s[12:13]
	v_lshl_add_u64 v[16:17], s[30:31], 0, v[16:17]
	global_load_lds_dwordx4 v[18:19], off
	v_lshl_add_u64 v[16:17], v[16:17], 0, s[12:13]
	s_mov_b32 m0, s47
	s_nop 0
	global_load_lds_dwordx4 v[16:17], off
	s_waitcnt vmcnt(8)
	s_waitcnt lgkmcnt(0)
	s_barrier
	s_setprio 1
	s_waitcnt lgkmcnt(0)
	v_mfma_scale_f32_16x16x128_f8f6f4 v[60:63], v[0:7], v[160:167], v[60:63], v143, v143 op_sel_hi:[0,0,0]
	v_mfma_scale_f32_16x16x128_f8f6f4 v[56:59], v[8:15], v[160:167], v[56:59], v143, v143 op_sel_hi:[0,0,0]
	v_mfma_scale_f32_16x16x128_f8f6f4 v[48:51], v[0:7], v[168:175], v[48:51], v143, v143 op_sel_hi:[0,0,0]
	v_mfma_scale_f32_16x16x128_f8f6f4 v[40:43], v[8:15], v[168:175], v[196:199], v143, v143 op_sel_hi:[0,0,0]
	v_mfma_scale_f32_16x16x128_f8f6f4 v[32:35], v[0:7], v[176:183], v[200:203], v143, v143 op_sel_hi:[0,0,0]
	v_mfma_scale_f32_16x16x128_f8f6f4 v[24:27], v[8:15], v[176:183], v[204:207], v143, v143 op_sel_hi:[0,0,0]
	v_mfma_scale_f32_16x16x128_f8f6f4 v[16:19], v[0:7], v[184:191], v[216:219], v143, v143 op_sel_hi:[0,0,0]
	v_mfma_scale_f32_16x16x128_f8f6f4 v[8:11], v[8:15], v[184:191], v[220:223], v143, v143 op_sel_hi:[0,0,0]
	s_setprio 0
	s_setprio 1
	v_mfma_scale_f32_16x16x128_f8f6f4 v[52:55], v[144:151], v[160:167], v[52:55], v143, v143 op_sel_hi:[0,0,0]
	v_mfma_scale_f32_16x16x128_f8f6f4 v[44:47], v[152:159], v[160:167], v[224:227], v143, v143 op_sel_hi:[0,0,0]
	v_mfma_scale_f32_16x16x128_f8f6f4 v[36:39], v[144:151], v[168:175], v[228:231], v143, v143 op_sel_hi:[0,0,0]
	v_mfma_scale_f32_16x16x128_f8f6f4 v[28:31], v[152:159], v[168:175], v[232:235], v143, v143 op_sel_hi:[0,0,0]
	v_mfma_scale_f32_16x16x128_f8f6f4 v[20:23], v[144:151], v[176:183], v[236:239], v143, v143 op_sel_hi:[0,0,0]
	v_mfma_scale_f32_16x16x128_f8f6f4 v[12:15], v[152:159], v[176:183], v[240:243], v143, v143 op_sel_hi:[0,0,0]
	v_mfma_scale_f32_16x16x128_f8f6f4 v[4:7], v[144:151], v[184:191], v[244:247], v143, v143 op_sel_hi:[0,0,0]
	v_mfma_scale_f32_16x16x128_f8f6f4 v[0:3], v[152:159], v[184:191], v[248:251], v143, v143 op_sel_hi:[0,0,0]
	s_setprio 0
	s_barrier
	s_add_i32 s49, s49, 2
	s_add_u32 s19, s19, 0x80000
	s_addc_u32 s48, s48, 0
	s_add_u32 s28, s28, 0x100
	s_addc_u32 s29, s29, 0
	s_sub_u32 s19, s19, s101
	s_subb_u32 s48, s48, 0
	s_sub_u32 s28, s28, s98
	s_subb_u32 s29, s29, 0
	s_add_i32 s99, s99, 2
	s_and_b32 s99, s99, 15
	s_cmp_gt_u32 s49, 13
	s_cbranch_scc0 .LBB0_1751
	s_and_b64 vcc, exec, s[14:15]
	s_cbranch_vccz .LBB0_1754
	s_barrier

.LBB0_2887:
	s_lshl_b32 s45, s12, 6
	s_lshl_b32 s15, s12, 13
	s_lshl_b32 s12, s33, 5
	s_and_b32 s46, s12, 0x60
	s_lshr_b32 s18, s46, 3
	s_add_u32 s12, s34, 0x80000
	v_mov_b32_e32 v1, v135
	v_mov_b32_e32 v2, v136
	s_addc_u32 s13, s35, 0
	s_add_i32 m0, s41, 0x18000
	s_waitcnt vmcnt(2)
	s_barrier
	v_mov_b32_e32 v128, v133
	global_load_lds_dwordx4 v1, s[12:13]
	s_add_i32 m0, s41, 0x1a000
	s_add_i32 s47, s41, 0x8000
	global_load_lds_dwordx4 v2, s[12:13]
	v_mov_b32_e32 v2, v134
	s_mov_b64 s[12:13], 0x80
	v_lshl_add_u64 v[4:5], s[30:31], 0, v[128:129]
	v_mov_b32_e32 v3, v129
	v_lshl_add_u64 v[4:5], v[4:5], 0, s[12:13]
	s_mov_b32 m0, s47
	v_lshl_add_u64 v[2:3], s[30:31], 0, v[2:3]
	s_add_i32 s48, s41, 0xa000
	global_load_lds_dwordx4 v[4:5], off
	v_lshl_add_u64 v[2:3], v[2:3], 0, s[12:13]
	s_mov_b32 m0, s48
	s_add_u32 s20, s34, 0x80800
	global_load_lds_dwordx4 v[2:3], off
	v_mov_b32_e32 v1, v135
	v_mov_b32_e32 v2, v136
	s_addc_u32 s21, s35, 0
	s_add_i32 m0, s41, 0x1c000
	s_sext_i32_i8 s29, s14
	global_load_lds_dwordx4 v1, s[20:21]
	s_add_i32 m0, s41, 0x1e000
	v_ashrrev_i32_e32 v1, 6, v0
	global_load_lds_dwordx4 v2, s[20:21]
	v_and_b32_e32 v2, 48, v0
	v_lshlrev_b32_e32 v4, 6, v0
	s_movk_i32 s14, 0x3c0
	v_lshlrev_b32_e32 v0, 2, v0
	s_cmpk_lt_u32 s90, 0x100
	v_lshl_add_u32 v3, v1, 10, s15
	v_and_or_b32 v2, v4, s14, v2
	v_and_b32_e32 v0, 32, v0
	v_add_lshl_u32 v1, v1, s18, 10
	s_waitcnt vmcnt(6)
	s_cselect_b64 s[14:15], -1, 0
	s_add_u32 s16, s16, 0x62358000
	v_bitop3_b32 v3, v2, v3, v0 bitop3:0xde
	v_bitop3_b32 v137, v2, v1, v0 bitop3:0xde
	s_addc_u32 s17, s17, 0
	s_add_i32 s50, 0, 0x10000
	s_add_i32 s51, 0, 0x14000
	s_mov_b32 s49, 0
	v_add_u32_e32 v138, s50, v137
	v_add_u32_e32 v139, s51, v137
	v_add_u32_e32 v140, 0, v3
	v_mov_b32_e32 v141, 0x7f7f7f7f
	s_mov_b32 s18, 0x3d000000
	s_mov_b64 s[24:25], s[34:35]
	s_mov_b64 s[22:23], s[30:31]
	s_barrier
	s_mov_b32 s99, 0
	s_mov_b32 s100, 0
	s_branch .LBB0_2890

.LBB0_2889:
	s_mov_b32 s99, s100
	s_andn2_b64 vcc, exec, s[26:27]
	s_mov_b32 s28, s20
	s_mov_b32 s29, s52
	s_mov_b64 s[34:35], s[24:25]
	s_mov_b64 s[30:31], s[22:23]
	s_cbranch_vccz .LBB0_2899
.LBB0_2890:
	s_add_i32 s49, s49, 1
	s_mul_i32 s21, s49, s62
	s_add_i32 s21, s21, s92
	s_cmpk_lt_i32 s21, 0x600
	s_cselect_b64 s[26:27], -1, 0
	s_cmpk_gt_i32 s21, 0x5ff
	s_cbranch_scc1 .LBB0_2892
	s_mul_hi_i32 s20, s21, 0x2aaaaaab
	s_lshr_b32 s22, s20, 31
	s_ashr_i32 s20, s20, 4
	s_add_i32 s24, s20, s22
	s_mul_i32 s20, s24, 0x60
	s_sub_i32 s20, s21, s20
	s_mul_i32 s21, s20, 43
	s_bfe_u32 s22, s21, 0x1000f
	s_bfe_u32 s21, s21, 0x80008
	s_add_i32 s36, s21, s22
	s_mul_i32 s22, s36, 6
	s_sub_i32 s20, s20, s22
	s_mul_i32 s21, s24, 6
	s_sext_i32_i8 s20, s20
	s_add_i32 s20, s21, s20
	s_ashr_i32 s21, s20, 31
	s_lshl_b64 s[22:23], s[20:21], 19
	s_add_u32 s22, s19, s22
	s_sext_i32_i8 s52, s36
	s_addc_u32 s23, s38, s23
	s_ashr_i32 s25, s24, 31
	s_bfe_i64 s[36:37], s[36:37], 0x80000
	s_lshl_b64 s[24:25], s[24:25], 23
	s_lshl_b64 s[36:37], s[36:37], 12
	s_add_u32 s21, s39, s24
	s_addc_u32 s24, s40, s25
	s_add_u32 s21, s21, s36
	s_addc_u32 s25, s24, s37
	s_add_u32 s24, s21, 0x8000000
	s_addc_u32 s25, s25, 0
	s_add_i32 s100, s20, s52
	s_and_b32 s100, s100, 3
	s_lshl_b32 s100, s100, 2
	s_lshl_b32 s98, s100, 7
	s_add_u32 s22, s22, s98
	s_addc_u32 s23, s23, 0
	s_lshl_b32 s98, s100, 19
	s_add_u32 s24, s24, s98
	s_addc_u32 s25, s25, 0

.LBB0_2893:
	ds_read_b128 v[142:145], v138
	ds_read_b128 v[146:149], v138 offset:1024
	ds_read_b128 v[150:153], v138 offset:2048
	ds_read_b128 v[154:157], v138 offset:3072
	ds_read_b128 v[158:161], v139
	ds_read_b128 v[162:165], v139 offset:1024
	ds_read_b128 v[166:169], v139 offset:2048
	ds_read_b128 v[170:173], v139 offset:3072
	s_add_u32 s34, s30, 0xfffc0080
	s_addc_u32 s35, s31, -1
	s_cmp_eq_u32 s99, 14
	s_cselect_b32 s98, 0x800, 0
	s_lshl_b32 s101, s98, 12
	s_sub_u32 s34, s34, s98
	s_subb_u32 s35, s35, 0
	s_sub_u32 s36, s21, s101
	s_subb_u32 s37, s53, 0
	s_cmp_eq_u32 s54, 12
	s_cselect_b32 s35, s23, s35
	s_cselect_b32 s34, s22, s34
	s_cselect_b32 s37, s25, s37
	s_cselect_b32 s36, s24, s36
	v_mov_b32_e32 v128, v133
	v_mov_b32_e32 v130, v134
	s_add_i32 m0, s41, 0xc000
	ds_read_b128 v[174:177], v140
	ds_read_b128 v[178:181], v140 offset:1024
	ds_read_b128 v[182:185], v140 offset:2048
	ds_read_b128 v[186:189], v140 offset:3072
	ds_read_b128 v[190:193], v140 offset:4096
	ds_read_b128 v[194:197], v140 offset:5120
	ds_read_b128 v[198:201], v140 offset:6144
	ds_read_b128 v[202:205], v140 offset:7168
	s_nop 0
	global_load_lds_dwordx4 v128, s[30:31]
	s_add_i32 m0, s41, 0xe000
	s_nop 0
	global_load_lds_dwordx4 v130, s[30:31]
	s_waitcnt vmcnt(8)
	s_waitcnt lgkmcnt(0)
	s_barrier
	s_setprio 1
	s_waitcnt lgkmcnt(0)
	v_mfma_scale_f32_16x16x128_f8f6f4 v[124:127], v[142:149], v[174:181], v[124:127], v141, v141 op_sel_hi:[0,0,0]
	v_mfma_scale_f32_16x16x128_f8f6f4 v[116:119], v[150:157], v[174:181], v[116:119], v141, v141 op_sel_hi:[0,0,0]
	v_mfma_scale_f32_16x16x128_f8f6f4 v[108:111], v[142:149], v[182:189], v[108:111], v141, v141 op_sel_hi:[0,0,0]
	v_mfma_scale_f32_16x16x128_f8f6f4 v[100:103], v[150:157], v[182:189], v[100:103], v141, v141 op_sel_hi:[0,0,0]
	v_mfma_scale_f32_16x16x128_f8f6f4 v[206:209], v[142:149], v[190:197], v[92:95], v141, v141 op_sel_hi:[0,0,0]
	v_mfma_scale_f32_16x16x128_f8f6f4 v[210:213], v[150:157], v[190:197], v[84:87], v141, v141 op_sel_hi:[0,0,0]
	v_mfma_scale_f32_16x16x128_f8f6f4 v[214:217], v[142:149], v[198:205], v[76:79], v141, v141 op_sel_hi:[0,0,0]
	v_mfma_scale_f32_16x16x128_f8f6f4 v[218:221], v[150:157], v[198:205], v[68:71], v141, v141 op_sel_hi:[0,0,0]
	s_setprio 0
	s_setprio 1
	v_mfma_scale_f32_16x16x128_f8f6f4 v[120:123], v[158:165], v[174:181], v[120:123], v141, v141 op_sel_hi:[0,0,0]
	v_mfma_scale_f32_16x16x128_f8f6f4 v[112:115], v[166:173], v[174:181], v[112:115], v141, v141 op_sel_hi:[0,0,0]
	v_mfma_scale_f32_16x16x128_f8f6f4 v[104:107], v[158:165], v[182:189], v[104:107], v141, v141 op_sel_hi:[0,0,0]
	v_mfma_scale_f32_16x16x128_f8f6f4 v[96:99], v[166:173], v[182:189], v[96:99], v141, v141 op_sel_hi:[0,0,0]
	v_mfma_scale_f32_16x16x128_f8f6f4 v[174:177], v[158:165], v[190:197], v[88:91], v141, v141 op_sel_hi:[0,0,0]
	v_mfma_scale_f32_16x16x128_f8f6f4 v[178:181], v[166:173], v[190:197], v[80:83], v141, v141 op_sel_hi:[0,0,0]
	v_mfma_scale_f32_16x16x128_f8f6f4 v[182:185], v[158:165], v[198:205], v[72:75], v141, v141 op_sel_hi:[0,0,0]
	v_mfma_scale_f32_16x16x128_f8f6f4 v[186:189], v[166:173], v[198:205], v[64:67], v141, v141 op_sel_hi:[0,0,0]
	s_setprio 0
	s_barrier
	s_add_i32 s55, s50, s3
	v_mov_b32_e32 v128, v135
	v_mov_b32_e32 v130, v136
	s_mov_b32 m0, s55
	s_nop 0
	ds_read_b128 v[64:67], v140 offset:16384
	ds_read_b128 v[68:71], v140 offset:17408
	ds_read_b128 v[72:75], v140 offset:18432
	ds_read_b128 v[76:79], v140 offset:19456
	ds_read_b128 v[80:83], v140 offset:20480
	ds_read_b128 v[84:87], v140 offset:21504
	ds_read_b128 v[88:91], v140 offset:22528
	ds_read_b128 v[92:95], v140 offset:23552
	v_mov_b32_e32 v131, v129
	global_load_lds_dwordx4 v128, s[36:37]
	s_add_i32 m0, s55, 0x2000
	v_mov_b32_e32 v128, v135
	global_load_lds_dwordx4 v130, s[36:37]
	v_mov_b32_e32 v130, v136
	s_add_i32 s55, s51, s3
	v_lshl_add_u64 v[190:191], s[36:37], 0, v[128:129]
	v_lshl_add_u64 v[190:191], v[190:191], 0, s[8:9]
	s_mov_b32 m0, s55
	v_lshl_add_u64 v[130:131], s[36:37], 0, v[130:131]
	global_load_lds_dwordx4 v[190:191], off
	v_lshl_add_u64 v[130:131], v[130:131], 0, s[8:9]
	s_add_i32 m0, s55, 0x2000
	v_mov_b32_e32 v128, v133
	global_load_lds_dwordx4 v[130:131], off
	v_mov_b32_e32 v130, v134
	s_mov_b32 m0, s41
	s_nop 0
	global_load_lds_dwordx4 v128, s[34:35]
	s_mov_b32 m0, s42
	s_nop 0
	global_load_lds_dwordx4 v130, s[34:35]
	s_waitcnt vmcnt(8)
	s_waitcnt lgkmcnt(0)
	s_barrier
	s_setprio 1
	s_waitcnt lgkmcnt(0)
	v_mfma_scale_f32_16x16x128_f8f6f4 v[60:63], v[142:149], v[64:71], v[60:63], v141, v141 op_sel_hi:[0,0,0]
	v_mfma_scale_f32_16x16x128_f8f6f4 v[52:55], v[150:157], v[64:71], v[52:55], v141, v141 op_sel_hi:[0,0,0]
	v_mfma_scale_f32_16x16x128_f8f6f4 v[44:47], v[142:149], v[72:79], v[44:47], v141, v141 op_sel_hi:[0,0,0]
	v_mfma_scale_f32_16x16x128_f8f6f4 v[198:201], v[150:157], v[72:79], v[36:39], v141, v141 op_sel_hi:[0,0,0]
	v_mfma_scale_f32_16x16x128_f8f6f4 v[202:205], v[142:149], v[80:87], v[28:31], v141, v141 op_sel_hi:[0,0,0]
	v_mfma_scale_f32_16x16x128_f8f6f4 v[222:225], v[150:157], v[80:87], v[20:23], v141, v141 op_sel_hi:[0,0,0]
	v_mfma_scale_f32_16x16x128_f8f6f4 v[226:229], v[142:149], v[88:95], v[12:15], v141, v141 op_sel_hi:[0,0,0]
	v_mfma_scale_f32_16x16x128_f8f6f4 v[230:233], v[150:157], v[88:95], v[4:7], v141, v141 op_sel_hi:[0,0,0]
	s_setprio 0
	s_setprio 1
	v_mfma_scale_f32_16x16x128_f8f6f4 v[56:59], v[158:165], v[64:71], v[56:59], v141, v141 op_sel_hi:[0,0,0]
	v_mfma_scale_f32_16x16x128_f8f6f4 v[48:51], v[166:173], v[64:71], v[48:51], v141, v141 op_sel_hi:[0,0,0]
	v_mfma_scale_f32_16x16x128_f8f6f4 v[40:43], v[158:165], v[72:79], v[40:43], v141, v141 op_sel_hi:[0,0,0]
	v_mfma_scale_f32_16x16x128_f8f6f4 v[234:237], v[166:173], v[72:79], v[32:35], v141, v141 op_sel_hi:[0,0,0]
	v_mfma_scale_f32_16x16x128_f8f6f4 v[238:241], v[158:165], v[80:87], v[24:27], v141, v141 op_sel_hi:[0,0,0]
	v_mfma_scale_f32_16x16x128_f8f6f4 v[242:245], v[166:173], v[80:87], v[16:19], v141, v141 op_sel_hi:[0,0,0]
	v_mfma_scale_f32_16x16x128_f8f6f4 v[246:249], v[158:165], v[88:95], v[8:11], v141, v141 op_sel_hi:[0,0,0]
	v_mfma_scale_f32_16x16x128_f8f6f4 v[250:253], v[166:173], v[88:95], v[0:3], v141, v141 op_sel_hi:[0,0,0]
	s_setprio 0
	s_barrier
	s_add_i32 s55, 0, 0x18000
	s_nop 2
	v_add_u32_e32 v8, s55, v137
	s_add_i32 s63, 0, 0x1c000
	ds_read_b128 v[0:3], v8
	ds_read_b128 v[4:7], v8 offset:1024
	ds_read_b128 v[142:145], v8 offset:2048
	ds_read_b128 v[146:149], v8 offset:3072
	v_add_u32_e32 v8, s63, v137
	ds_read_b128 v[150:153], v8
	ds_read_b128 v[154:157], v8 offset:1024
	ds_read_b128 v[158:161], v8 offset:2048
	ds_read_b128 v[162:165], v8 offset:3072
	s_add_u32 s64, s34, 0x40000
	v_mov_b32_e32 v64, v133
	v_mov_b32_e32 v65, v134
	s_addc_u32 s65, s35, 0
	s_mov_b32 m0, s43
	ds_read_b128 v[8:11], v140 offset:32768
	ds_read_b128 v[12:15], v140 offset:33792
	ds_read_b128 v[16:19], v140 offset:34816
	ds_read_b128 v[20:23], v140 offset:35840
	ds_read_b128 v[24:27], v140 offset:36864
	ds_read_b128 v[28:31], v140 offset:37888
	ds_read_b128 v[32:35], v140 offset:38912
	ds_read_b128 v[36:39], v140 offset:39936
	s_nop 0
	global_load_lds_dwordx4 v64, s[64:65]
	s_mov_b32 m0, s44
	s_nop 0
	global_load_lds_dwordx4 v65, s[64:65]
	s_waitcnt vmcnt(8)
	s_waitcnt lgkmcnt(0)
	s_barrier
	s_setprio 1
	s_waitcnt lgkmcnt(0)
	v_mfma_scale_f32_16x16x128_f8f6f4 v[124:127], v[0:7], v[8:15], v[124:127], v141, v141 op_sel_hi:[0,0,0]
	v_mfma_scale_f32_16x16x128_f8f6f4 v[116:119], v[142:149], v[8:15], v[116:119], v141, v141 op_sel_hi:[0,0,0]
	v_mfma_scale_f32_16x16x128_f8f6f4 v[108:111], v[0:7], v[16:23], v[108:111], v141, v141 op_sel_hi:[0,0,0]
	v_mfma_scale_f32_16x16x128_f8f6f4 v[100:103], v[142:149], v[16:23], v[100:103], v141, v141 op_sel_hi:[0,0,0]
	v_mfma_scale_f32_16x16x128_f8f6f4 v[92:95], v[0:7], v[24:31], v[206:209], v141, v141 op_sel_hi:[0,0,0]
	v_mfma_scale_f32_16x16x128_f8f6f4 v[84:87], v[142:149], v[24:31], v[210:213], v141, v141 op_sel_hi:[0,0,0]
	v_mfma_scale_f32_16x16x128_f8f6f4 v[76:79], v[0:7], v[32:39], v[214:217], v141, v141 op_sel_hi:[0,0,0]
	v_mfma_scale_f32_16x16x128_f8f6f4 v[68:71], v[142:149], v[32:39], v[218:221], v141, v141 op_sel_hi:[0,0,0]
	s_setprio 0
	s_setprio 1
	v_mfma_scale_f32_16x16x128_f8f6f4 v[120:123], v[150:157], v[8:15], v[120:123], v141, v141 op_sel_hi:[0,0,0]
	v_mfma_scale_f32_16x16x128_f8f6f4 v[112:115], v[158:165], v[8:15], v[112:115], v141, v141 op_sel_hi:[0,0,0]
	v_mfma_scale_f32_16x16x128_f8f6f4 v[104:107], v[150:157], v[16:23], v[104:107], v141, v141 op_sel_hi:[0,0,0]
	v_mfma_scale_f32_16x16x128_f8f6f4 v[96:99], v[158:165], v[16:23], v[96:99], v141, v141 op_sel_hi:[0,0,0]
	v_mfma_scale_f32_16x16x128_f8f6f4 v[88:91], v[150:157], v[24:31], v[174:177], v141, v141 op_sel_hi:[0,0,0]
	v_mfma_scale_f32_16x16x128_f8f6f4 v[80:83], v[158:165], v[24:31], v[178:181], v141, v141 op_sel_hi:[0,0,0]
	v_mfma_scale_f32_16x16x128_f8f6f4 v[72:75], v[150:157], v[32:39], v[182:185], v141, v141 op_sel_hi:[0,0,0]
	v_mfma_scale_f32_16x16x128_f8f6f4 v[64:67], v[158:165], v[32:39], v[186:189], v141, v141 op_sel_hi:[0,0,0]
	s_setprio 0
	s_barrier
	s_add_u32 s64, s36, 0x80000
	s_addc_u32 s65, s37, 0
	s_add_i32 s55, s55, s3
	v_mov_b32_e32 v8, v135
	v_mov_b32_e32 v9, v136
	s_mov_b32 m0, s55
	ds_read_b128 v[166:169], v140 offset:49152
	ds_read_b128 v[170:173], v140 offset:50176
	ds_read_b128 v[174:177], v140 offset:51200
	ds_read_b128 v[178:181], v140 offset:52224
	ds_read_b128 v[182:185], v140 offset:53248
	ds_read_b128 v[186:189], v140 offset:54272
	ds_read_b128 v[190:193], v140 offset:55296
	ds_read_b128 v[194:197], v140 offset:56320
	v_mov_b32_e32 v128, v133
	global_load_lds_dwordx4 v8, s[64:65]
	s_add_i32 m0, s55, 0x2000
	s_add_u32 s36, s36, 0x80800
	global_load_lds_dwordx4 v9, s[64:65]
	v_mov_b32_e32 v8, v135
	v_mov_b32_e32 v9, v136
	s_addc_u32 s37, s37, 0
	s_add_i32 s55, s63, s3
	s_mov_b32 m0, s55
	s_nop 0
	global_load_lds_dwordx4 v8, s[36:37]
	s_add_i32 m0, s55, 0x2000
	v_mov_b32_e32 v8, v134
	global_load_lds_dwordx4 v9, s[36:37]
	v_mov_b32_e32 v9, v129
	v_lshl_add_u64 v[10:11], s[34:35], 0, v[128:129]
	v_lshl_add_u64 v[10:11], v[10:11], 0, s[12:13]
	s_mov_b32 m0, s47
	v_lshl_add_u64 v[8:9], s[34:35], 0, v[8:9]
	global_load_lds_dwordx4 v[10:11], off
	v_lshl_add_u64 v[8:9], v[8:9], 0, s[12:13]
	s_mov_b32 m0, s48
	s_nop 0
	global_load_lds_dwordx4 v[8:9], off
	s_waitcnt vmcnt(8)
	s_waitcnt lgkmcnt(0)
	s_barrier
	s_setprio 1
	s_waitcnt lgkmcnt(0)
	v_mfma_scale_f32_16x16x128_f8f6f4 v[60:63], v[0:7], v[166:173], v[60:63], v141, v141 op_sel_hi:[0,0,0]
	v_mfma_scale_f32_16x16x128_f8f6f4 v[52:55], v[142:149], v[166:173], v[52:55], v141, v141 op_sel_hi:[0,0,0]
	v_mfma_scale_f32_16x16x128_f8f6f4 v[44:47], v[0:7], v[174:181], v[44:47], v141, v141 op_sel_hi:[0,0,0]
	v_mfma_scale_f32_16x16x128_f8f6f4 v[36:39], v[142:149], v[174:181], v[198:201], v141, v141 op_sel_hi:[0,0,0]
	v_mfma_scale_f32_16x16x128_f8f6f4 v[28:31], v[0:7], v[182:189], v[202:205], v141, v141 op_sel_hi:[0,0,0]
	v_mfma_scale_f32_16x16x128_f8f6f4 v[20:23], v[142:149], v[182:189], v[222:225], v141, v141 op_sel_hi:[0,0,0]
	v_mfma_scale_f32_16x16x128_f8f6f4 v[12:15], v[0:7], v[190:197], v[226:229], v141, v141 op_sel_hi:[0,0,0]
	v_mfma_scale_f32_16x16x128_f8f6f4 v[4:7], v[142:149], v[190:197], v[230:233], v141, v141 op_sel_hi:[0,0,0]
	s_setprio 0
	s_setprio 1
	v_mfma_scale_f32_16x16x128_f8f6f4 v[56:59], v[150:157], v[166:173], v[56:59], v141, v141 op_sel_hi:[0,0,0]
	v_mfma_scale_f32_16x16x128_f8f6f4 v[48:51], v[158:165], v[166:173], v[48:51], v141, v141 op_sel_hi:[0,0,0]
	v_mfma_scale_f32_16x16x128_f8f6f4 v[40:43], v[150:157], v[174:181], v[40:43], v141, v141 op_sel_hi:[0,0,0]
	v_mfma_scale_f32_16x16x128_f8f6f4 v[32:35], v[158:165], v[174:181], v[234:237], v141, v141 op_sel_hi:[0,0,0]
	v_mfma_scale_f32_16x16x128_f8f6f4 v[24:27], v[150:157], v[182:189], v[238:241], v141, v141 op_sel_hi:[0,0,0]
	v_mfma_scale_f32_16x16x128_f8f6f4 v[16:19], v[158:165], v[182:189], v[242:245], v141, v141 op_sel_hi:[0,0,0]
	v_mfma_scale_f32_16x16x128_f8f6f4 v[8:11], v[150:157], v[190:197], v[246:249], v141, v141 op_sel_hi:[0,0,0]
	v_mfma_scale_f32_16x16x128_f8f6f4 v[0:3], v[158:165], v[190:197], v[250:253], v141, v141 op_sel_hi:[0,0,0]
	s_setprio 0
	s_barrier
	s_add_i32 s54, s54, 2
	s_add_u32 s21, s21, 0x100000
	s_addc_u32 s53, s53, 0
	s_add_u32 s30, s30, 0x100
	s_addc_u32 s31, s31, 0
	s_sub_u32 s21, s21, s101
	s_subb_u32 s53, s53, 0
	s_sub_u32 s30, s30, s98
	s_subb_u32 s31, s31, 0
	s_add_i32 s99, s99, 2
	s_and_b32 s99, s99, 15
	s_cmp_gt_u32 s54, 13
	s_cbranch_scc0 .LBB0_2893
	s_and_b64 vcc, exec, s[14:15]
	s_cbranch_vccz .LBB0_2896
	s_barrier

.LBB0_2958:
	s_lshl_b32 s44, s12, 6
	s_lshl_b32 s15, s12, 13
	s_lshl_b32 s12, s33, 5
	s_and_b32 s45, s12, 0x60
	s_lshr_b32 s20, s45, 3
	s_add_u32 s12, s30, 0x40000
	v_mov_b32_e32 v1, v137
	v_mov_b32_e32 v2, v138
	s_addc_u32 s13, s31, 0
	s_add_i32 m0, s40, 0x18000
	s_waitcnt vmcnt(2)
	s_barrier
	v_mov_b32_e32 v128, v135
	global_load_lds_dwordx4 v1, s[12:13]
	s_add_i32 m0, s40, 0x1a000
	s_add_i32 s46, s40, 0x8000
	global_load_lds_dwordx4 v2, s[12:13]
	v_mov_b32_e32 v2, v136
	s_mov_b64 s[12:13], 0x80
	v_lshl_add_u64 v[4:5], s[28:29], 0, v[128:129]
	v_mov_b32_e32 v3, v129
	v_lshl_add_u64 v[4:5], v[4:5], 0, s[12:13]
	s_mov_b32 m0, s46
	v_lshl_add_u64 v[2:3], s[28:29], 0, v[2:3]
	s_add_i32 s47, s40, 0xa000
	global_load_lds_dwordx4 v[4:5], off
	v_lshl_add_u64 v[2:3], v[2:3], 0, s[12:13]
	s_mov_b32 m0, s47
	s_add_u32 s18, s30, 0x40800
	global_load_lds_dwordx4 v[2:3], off
	v_mov_b32_e32 v1, v137
	v_mov_b32_e32 v2, v138
	s_addc_u32 s19, s31, 0
	s_add_i32 m0, s40, 0x1c000
	s_sext_i32_i8 s27, s14
	global_load_lds_dwordx4 v1, s[18:19]
	s_add_i32 m0, s40, 0x1e000
	v_ashrrev_i32_e32 v1, 6, v0
	global_load_lds_dwordx4 v2, s[18:19]
	v_and_b32_e32 v2, 48, v0
	v_lshlrev_b32_e32 v4, 6, v0
	s_movk_i32 s14, 0x3c0
	v_lshlrev_b32_e32 v0, 2, v0
	s_cmpk_lt_u32 s90, 0x100
	v_lshl_add_u32 v3, v1, 10, s15
	v_and_or_b32 v2, v4, s14, v2
	v_and_b32_e32 v0, 32, v0
	v_add_lshl_u32 v1, v1, s20, 10
	s_waitcnt vmcnt(6)
	s_cselect_b64 s[14:15], -1, 0
	s_add_u32 s16, s16, 0x68358000
	v_bitop3_b32 v3, v2, v3, v0 bitop3:0xde
	v_bitop3_b32 v139, v2, v1, v0 bitop3:0xde
	s_addc_u32 s17, s17, 0
	s_add_i32 s49, 0, 0x10000
	s_add_i32 s50, 0, 0x14000
	s_mov_b32 s48, 0
	v_add_u32_e32 v140, s49, v139
	v_add_u32_e32 v141, s50, v139
	v_add_u32_e32 v142, 0, v3
	v_mov_b32_e32 v143, 0x7f7f7f7f
	s_mov_b64 s[22:23], s[30:31]
	s_mov_b64 s[20:21], s[28:29]
	s_barrier
	s_mov_b32 s99, 0
	s_mov_b32 s100, 0
	s_branch .LBB0_2961

.LBB0_2960:
	s_mov_b32 s99, s100
	s_andn2_b64 vcc, exec, s[24:25]
	s_mov_b32 s26, s18
	s_mov_b32 s27, s51
	s_mov_b64 s[30:31], s[22:23]
	s_mov_b64 s[28:29], s[20:21]
	s_cbranch_vccz .LBB0_2970
.LBB0_2961:
	s_add_i32 s48, s48, 1
	s_mul_i32 s19, s48, s62
	s_add_i32 s19, s19, s92
	s_cmpk_lt_i32 s19, 0x300
	s_cselect_b64 s[24:25], -1, 0
	s_cmpk_gt_i32 s19, 0x2ff
	s_cbranch_scc1 .LBB0_2963
	s_mul_hi_i32 s18, s19, 0x2aaaaaab
	s_lshr_b32 s20, s18, 31
	s_ashr_i32 s18, s18, 3
	s_add_i32 s22, s18, s20
	s_mul_i32 s18, s22, 48
	s_sub_i32 s18, s19, s18
	s_mul_i32 s19, s18, 43
	s_bfe_u32 s20, s19, 0x1000f
	s_bfe_u32 s19, s19, 0x80008
	s_add_i32 s34, s19, s20
	s_mul_i32 s20, s34, 6
	s_sub_i32 s18, s18, s20
	s_mul_i32 s19, s22, 6
	s_sext_i32_i8 s18, s18
	s_add_i32 s18, s19, s18
	s_ashr_i32 s19, s18, 31
	s_lshl_b64 s[20:21], s[18:19], 19
	s_add_u32 s20, s36, s20
	s_sext_i32_i8 s51, s34
	s_addc_u32 s21, s37, s21
	s_ashr_i32 s23, s22, 31
	s_bfe_i64 s[34:35], s[34:35], 0x80000
	s_lshl_b64 s[22:23], s[22:23], 22
	s_lshl_b64 s[34:35], s[34:35], 12
	s_add_u32 s19, s38, s22
	s_addc_u32 s22, s39, s23
	s_add_u32 s19, s19, s34
	s_addc_u32 s23, s22, s35
	s_add_u32 s22, s19, 0x4000000
	s_addc_u32 s23, s23, 0
	s_add_i32 s100, s18, s51
	s_and_b32 s100, s100, 3
	s_lshl_b32 s100, s100, 2
	s_lshl_b32 s98, s100, 7
	s_add_u32 s20, s20, s98
	s_addc_u32 s21, s21, 0
	s_lshl_b32 s98, s100, 18
	s_add_u32 s22, s22, s98
	s_addc_u32 s23, s23, 0

.LBB0_2964:
	ds_read_b128 v[144:147], v140
	ds_read_b128 v[148:151], v140 offset:1024
	ds_read_b128 v[152:155], v140 offset:2048
	ds_read_b128 v[156:159], v140 offset:3072
	ds_read_b128 v[160:163], v141
	ds_read_b128 v[164:167], v141 offset:1024
	ds_read_b128 v[168:171], v141 offset:2048
	ds_read_b128 v[172:175], v141 offset:3072
	s_add_u32 s30, s28, 0xfffc0080
	s_addc_u32 s31, s29, -1
	s_cmp_eq_u32 s99, 14
	s_cselect_b32 s98, 0x800, 0
	s_lshl_b32 s101, s98, 11
	s_sub_u32 s30, s30, s98
	s_subb_u32 s31, s31, 0
	s_sub_u32 s34, s19, s101
	s_subb_u32 s35, s52, 0
	s_cmp_eq_u32 s53, 12
	s_cselect_b32 s31, s21, s31
	s_cselect_b32 s30, s20, s30
	s_cselect_b32 s35, s23, s35
	s_cselect_b32 s34, s22, s34
	v_mov_b32_e32 v128, v135
	v_mov_b32_e32 v130, v136
	s_add_i32 m0, s40, 0xc000
	ds_read_b128 v[176:179], v142
	ds_read_b128 v[180:183], v142 offset:1024
	ds_read_b128 v[184:187], v142 offset:2048
	ds_read_b128 v[188:191], v142 offset:3072
	ds_read_b128 v[192:195], v142 offset:4096
	ds_read_b128 v[196:199], v142 offset:5120
	ds_read_b128 v[200:203], v142 offset:6144
	ds_read_b128 v[204:207], v142 offset:7168
	s_nop 0
	global_load_lds_dwordx4 v128, s[28:29]
	s_add_i32 m0, s40, 0xe000
	s_nop 0
	global_load_lds_dwordx4 v130, s[28:29]
	s_waitcnt vmcnt(8)
	s_waitcnt lgkmcnt(0)
	s_barrier
	s_setprio 1
	s_waitcnt lgkmcnt(0)
	v_mfma_scale_f32_16x16x128_f8f6f4 v[124:127], v[144:151], v[176:183], v[124:127], v143, v143 op_sel_hi:[0,0,0]
	v_mfma_scale_f32_16x16x128_f8f6f4 v[120:123], v[152:159], v[176:183], v[120:123], v143, v143 op_sel_hi:[0,0,0]
	v_mfma_scale_f32_16x16x128_f8f6f4 v[112:115], v[144:151], v[184:191], v[112:115], v143, v143 op_sel_hi:[0,0,0]
	v_mfma_scale_f32_16x16x128_f8f6f4 v[104:107], v[152:159], v[184:191], v[104:107], v143, v143 op_sel_hi:[0,0,0]
	v_mfma_scale_f32_16x16x128_f8f6f4 v[96:99], v[144:151], v[192:199], v[96:99], v143, v143 op_sel_hi:[0,0,0]
	v_mfma_scale_f32_16x16x128_f8f6f4 v[130:133], v[152:159], v[192:199], v[88:91], v143, v143 op_sel_hi:[0,0,0]
	v_mfma_scale_f32_16x16x128_f8f6f4 v[208:211], v[144:151], v[200:207], v[80:83], v143, v143 op_sel_hi:[0,0,0]
	v_mfma_scale_f32_16x16x128_f8f6f4 v[212:215], v[152:159], v[200:207], v[72:75], v143, v143 op_sel_hi:[0,0,0]
	s_setprio 0
	s_setprio 1
	v_mfma_scale_f32_16x16x128_f8f6f4 v[116:119], v[160:167], v[176:183], v[116:119], v143, v143 op_sel_hi:[0,0,0]
	v_mfma_scale_f32_16x16x128_f8f6f4 v[108:111], v[168:175], v[176:183], v[108:111], v143, v143 op_sel_hi:[0,0,0]
	v_mfma_scale_f32_16x16x128_f8f6f4 v[100:103], v[160:167], v[184:191], v[100:103], v143, v143 op_sel_hi:[0,0,0]
	v_mfma_scale_f32_16x16x128_f8f6f4 v[176:179], v[168:175], v[184:191], v[92:95], v143, v143 op_sel_hi:[0,0,0]
	v_mfma_scale_f32_16x16x128_f8f6f4 v[180:183], v[160:167], v[192:199], v[84:87], v143, v143 op_sel_hi:[0,0,0]
	v_mfma_scale_f32_16x16x128_f8f6f4 v[184:187], v[168:175], v[192:199], v[76:79], v143, v143 op_sel_hi:[0,0,0]
	v_mfma_scale_f32_16x16x128_f8f6f4 v[188:191], v[160:167], v[200:207], v[68:71], v143, v143 op_sel_hi:[0,0,0]
	v_mfma_scale_f32_16x16x128_f8f6f4 v[192:195], v[168:175], v[200:207], v[64:67], v143, v143 op_sel_hi:[0,0,0]
	s_setprio 0
	s_barrier
	s_add_i32 s54, s49, s3
	v_mov_b32_e32 v128, v137
	v_mov_b32_e32 v196, v138
	s_mov_b32 m0, s54
	s_nop 0
	ds_read_b128 v[64:67], v142 offset:16384
	ds_read_b128 v[68:71], v142 offset:17408
	ds_read_b128 v[72:75], v142 offset:18432
	ds_read_b128 v[76:79], v142 offset:19456
	ds_read_b128 v[80:83], v142 offset:20480
	ds_read_b128 v[84:87], v142 offset:21504
	ds_read_b128 v[88:91], v142 offset:22528
	ds_read_b128 v[92:95], v142 offset:23552
	v_mov_b32_e32 v197, v129
	global_load_lds_dwordx4 v128, s[34:35]
	s_add_i32 m0, s54, 0x2000
	v_mov_b32_e32 v128, v137
	global_load_lds_dwordx4 v196, s[34:35]
	v_mov_b32_e32 v196, v138
	s_add_i32 s54, s50, s3
	v_lshl_add_u64 v[198:199], s[34:35], 0, v[128:129]
	v_lshl_add_u64 v[198:199], v[198:199], 0, s[8:9]
	s_mov_b32 m0, s54
	v_lshl_add_u64 v[196:197], s[34:35], 0, v[196:197]
	global_load_lds_dwordx4 v[198:199], off
	v_lshl_add_u64 v[196:197], v[196:197], 0, s[8:9]
	s_add_i32 m0, s54, 0x2000
	v_mov_b32_e32 v128, v135
	global_load_lds_dwordx4 v[196:197], off
	v_mov_b32_e32 v196, v136
	s_mov_b32 m0, s40
	s_nop 0
	global_load_lds_dwordx4 v128, s[30:31]
	s_mov_b32 m0, s41
	s_nop 0
	global_load_lds_dwordx4 v196, s[30:31]
	s_waitcnt vmcnt(8)
	s_waitcnt lgkmcnt(0)
	s_barrier
	s_setprio 1
	s_waitcnt lgkmcnt(0)
	v_mfma_scale_f32_16x16x128_f8f6f4 v[60:63], v[144:151], v[64:71], v[60:63], v143, v143 op_sel_hi:[0,0,0]
	v_mfma_scale_f32_16x16x128_f8f6f4 v[56:59], v[152:159], v[64:71], v[56:59], v143, v143 op_sel_hi:[0,0,0]
	v_mfma_scale_f32_16x16x128_f8f6f4 v[48:51], v[144:151], v[72:79], v[48:51], v143, v143 op_sel_hi:[0,0,0]
	v_mfma_scale_f32_16x16x128_f8f6f4 v[196:199], v[152:159], v[72:79], v[40:43], v143, v143 op_sel_hi:[0,0,0]
	v_mfma_scale_f32_16x16x128_f8f6f4 v[200:203], v[144:151], v[80:87], v[32:35], v143, v143 op_sel_hi:[0,0,0]
	v_mfma_scale_f32_16x16x128_f8f6f4 v[204:207], v[152:159], v[80:87], v[24:27], v143, v143 op_sel_hi:[0,0,0]
	v_mfma_scale_f32_16x16x128_f8f6f4 v[216:219], v[144:151], v[88:95], v[16:19], v143, v143 op_sel_hi:[0,0,0]
	v_mfma_scale_f32_16x16x128_f8f6f4 v[220:223], v[152:159], v[88:95], v[8:11], v143, v143 op_sel_hi:[0,0,0]
	s_setprio 0
	s_setprio 1
	v_mfma_scale_f32_16x16x128_f8f6f4 v[52:55], v[160:167], v[64:71], v[52:55], v143, v143 op_sel_hi:[0,0,0]
	v_mfma_scale_f32_16x16x128_f8f6f4 v[224:227], v[168:175], v[64:71], v[44:47], v143, v143 op_sel_hi:[0,0,0]
	v_mfma_scale_f32_16x16x128_f8f6f4 v[228:231], v[160:167], v[72:79], v[36:39], v143, v143 op_sel_hi:[0,0,0]
	v_mfma_scale_f32_16x16x128_f8f6f4 v[232:235], v[168:175], v[72:79], v[28:31], v143, v143 op_sel_hi:[0,0,0]
	v_mfma_scale_f32_16x16x128_f8f6f4 v[236:239], v[160:167], v[80:87], v[20:23], v143, v143 op_sel_hi:[0,0,0]
	v_mfma_scale_f32_16x16x128_f8f6f4 v[240:243], v[168:175], v[80:87], v[12:15], v143, v143 op_sel_hi:[0,0,0]
	v_mfma_scale_f32_16x16x128_f8f6f4 v[244:247], v[160:167], v[88:95], v[4:7], v143, v143 op_sel_hi:[0,0,0]
	v_mfma_scale_f32_16x16x128_f8f6f4 v[248:251], v[168:175], v[88:95], v[0:3], v143, v143 op_sel_hi:[0,0,0]
	s_setprio 0
	s_barrier
	s_add_i32 s63, 0, 0x18000
	s_add_i32 s64, 0, 0x1c000
	s_nop 0
	v_add_u32_e32 v12, s63, v139
	v_add_u32_e32 v16, s64, v139
	ds_read_b128 v[0:3], v12
	ds_read_b128 v[4:7], v12 offset:1024
	ds_read_b128 v[8:11], v12 offset:2048
	ds_read_b128 v[12:15], v12 offset:3072
	ds_read_b128 v[144:147], v16
	ds_read_b128 v[148:151], v16 offset:1024
	ds_read_b128 v[152:155], v16 offset:2048
	ds_read_b128 v[156:159], v16 offset:3072
	s_add_u32 s54, s30, 0x40000
	v_mov_b32_e32 v64, v135
	v_mov_b32_e32 v65, v136
	s_addc_u32 s55, s31, 0
	s_mov_b32 m0, s42
	ds_read_b128 v[16:19], v142 offset:32768
	ds_read_b128 v[20:23], v142 offset:33792
	ds_read_b128 v[24:27], v142 offset:34816
	ds_read_b128 v[28:31], v142 offset:35840
	ds_read_b128 v[32:35], v142 offset:36864
	ds_read_b128 v[36:39], v142 offset:37888
	ds_read_b128 v[40:43], v142 offset:38912
	ds_read_b128 v[44:47], v142 offset:39936
	s_nop 0
	global_load_lds_dwordx4 v64, s[54:55]
	s_mov_b32 m0, s43
	s_nop 0
	global_load_lds_dwordx4 v65, s[54:55]
	s_waitcnt vmcnt(8)
	s_waitcnt lgkmcnt(0)
	s_barrier
	s_setprio 1
	s_waitcnt lgkmcnt(0)
	v_mfma_scale_f32_16x16x128_f8f6f4 v[124:127], v[0:7], v[16:23], v[124:127], v143, v143 op_sel_hi:[0,0,0]
	v_mfma_scale_f32_16x16x128_f8f6f4 v[120:123], v[8:15], v[16:23], v[120:123], v143, v143 op_sel_hi:[0,0,0]
	v_mfma_scale_f32_16x16x128_f8f6f4 v[112:115], v[0:7], v[24:31], v[112:115], v143, v143 op_sel_hi:[0,0,0]
	v_mfma_scale_f32_16x16x128_f8f6f4 v[104:107], v[8:15], v[24:31], v[104:107], v143, v143 op_sel_hi:[0,0,0]
	v_mfma_scale_f32_16x16x128_f8f6f4 v[96:99], v[0:7], v[32:39], v[96:99], v143, v143 op_sel_hi:[0,0,0]
	v_mfma_scale_f32_16x16x128_f8f6f4 v[88:91], v[8:15], v[32:39], v[130:133], v143, v143 op_sel_hi:[0,0,0]
	v_mfma_scale_f32_16x16x128_f8f6f4 v[80:83], v[0:7], v[40:47], v[208:211], v143, v143 op_sel_hi:[0,0,0]
	v_mfma_scale_f32_16x16x128_f8f6f4 v[72:75], v[8:15], v[40:47], v[212:215], v143, v143 op_sel_hi:[0,0,0]
	s_setprio 0
	s_setprio 1
	v_mfma_scale_f32_16x16x128_f8f6f4 v[116:119], v[144:151], v[16:23], v[116:119], v143, v143 op_sel_hi:[0,0,0]
	v_mfma_scale_f32_16x16x128_f8f6f4 v[108:111], v[152:159], v[16:23], v[108:111], v143, v143 op_sel_hi:[0,0,0]
	v_mfma_scale_f32_16x16x128_f8f6f4 v[100:103], v[144:151], v[24:31], v[100:103], v143, v143 op_sel_hi:[0,0,0]
	v_mfma_scale_f32_16x16x128_f8f6f4 v[92:95], v[152:159], v[24:31], v[176:179], v143, v143 op_sel_hi:[0,0,0]
	v_mfma_scale_f32_16x16x128_f8f6f4 v[84:87], v[144:151], v[32:39], v[180:183], v143, v143 op_sel_hi:[0,0,0]
	v_mfma_scale_f32_16x16x128_f8f6f4 v[76:79], v[152:159], v[32:39], v[184:187], v143, v143 op_sel_hi:[0,0,0]
	v_mfma_scale_f32_16x16x128_f8f6f4 v[68:71], v[144:151], v[40:47], v[188:191], v143, v143 op_sel_hi:[0,0,0]
	v_mfma_scale_f32_16x16x128_f8f6f4 v[64:67], v[152:159], v[40:47], v[192:195], v143, v143 op_sel_hi:[0,0,0]
	s_setprio 0
	s_barrier
	s_add_u32 s54, s34, 0x40000
	s_addc_u32 s55, s35, 0
	s_add_i32 s63, s63, s3
	v_mov_b32_e32 v16, v137
	v_mov_b32_e32 v17, v138
	s_mov_b32 m0, s63
	ds_read_b128 v[160:163], v142 offset:49152
	ds_read_b128 v[164:167], v142 offset:50176
	ds_read_b128 v[168:171], v142 offset:51200
	ds_read_b128 v[172:175], v142 offset:52224
	ds_read_b128 v[176:179], v142 offset:53248
	ds_read_b128 v[180:183], v142 offset:54272
	ds_read_b128 v[184:187], v142 offset:55296
	ds_read_b128 v[188:191], v142 offset:56320
	v_mov_b32_e32 v128, v135
	global_load_lds_dwordx4 v16, s[54:55]
	s_add_i32 m0, s63, 0x2000
	s_add_u32 s34, s34, 0x40800
	global_load_lds_dwordx4 v17, s[54:55]
	v_mov_b32_e32 v16, v137
	v_mov_b32_e32 v17, v138
	s_addc_u32 s35, s35, 0
	s_add_i32 s54, s64, s3
	s_mov_b32 m0, s54
	s_nop 0
	global_load_lds_dwordx4 v16, s[34:35]
	s_add_i32 m0, s54, 0x2000
	v_mov_b32_e32 v16, v136
	global_load_lds_dwordx4 v17, s[34:35]
	v_mov_b32_e32 v17, v129
	v_lshl_add_u64 v[18:19], s[30:31], 0, v[128:129]
	v_lshl_add_u64 v[18:19], v[18:19], 0, s[12:13]
	s_mov_b32 m0, s46
	v_lshl_add_u64 v[16:17], s[30:31], 0, v[16:17]
	global_load_lds_dwordx4 v[18:19], off
	v_lshl_add_u64 v[16:17], v[16:17], 0, s[12:13]
	s_mov_b32 m0, s47
	s_nop 0
	global_load_lds_dwordx4 v[16:17], off
	s_waitcnt vmcnt(8)
	s_waitcnt lgkmcnt(0)
	s_barrier
	s_setprio 1
	s_waitcnt lgkmcnt(0)
	v_mfma_scale_f32_16x16x128_f8f6f4 v[60:63], v[0:7], v[160:167], v[60:63], v143, v143 op_sel_hi:[0,0,0]
	v_mfma_scale_f32_16x16x128_f8f6f4 v[56:59], v[8:15], v[160:167], v[56:59], v143, v143 op_sel_hi:[0,0,0]
	v_mfma_scale_f32_16x16x128_f8f6f4 v[48:51], v[0:7], v[168:175], v[48:51], v143, v143 op_sel_hi:[0,0,0]
	v_mfma_scale_f32_16x16x128_f8f6f4 v[40:43], v[8:15], v[168:175], v[196:199], v143, v143 op_sel_hi:[0,0,0]
	v_mfma_scale_f32_16x16x128_f8f6f4 v[32:35], v[0:7], v[176:183], v[200:203], v143, v143 op_sel_hi:[0,0,0]
	v_mfma_scale_f32_16x16x128_f8f6f4 v[24:27], v[8:15], v[176:183], v[204:207], v143, v143 op_sel_hi:[0,0,0]
	v_mfma_scale_f32_16x16x128_f8f6f4 v[16:19], v[0:7], v[184:191], v[216:219], v143, v143 op_sel_hi:[0,0,0]
	v_mfma_scale_f32_16x16x128_f8f6f4 v[8:11], v[8:15], v[184:191], v[220:223], v143, v143 op_sel_hi:[0,0,0]
	s_setprio 0
	s_setprio 1
	v_mfma_scale_f32_16x16x128_f8f6f4 v[52:55], v[144:151], v[160:167], v[52:55], v143, v143 op_sel_hi:[0,0,0]
	v_mfma_scale_f32_16x16x128_f8f6f4 v[44:47], v[152:159], v[160:167], v[224:227], v143, v143 op_sel_hi:[0,0,0]
	v_mfma_scale_f32_16x16x128_f8f6f4 v[36:39], v[144:151], v[168:175], v[228:231], v143, v143 op_sel_hi:[0,0,0]
	v_mfma_scale_f32_16x16x128_f8f6f4 v[28:31], v[152:159], v[168:175], v[232:235], v143, v143 op_sel_hi:[0,0,0]
	v_mfma_scale_f32_16x16x128_f8f6f4 v[20:23], v[144:151], v[176:183], v[236:239], v143, v143 op_sel_hi:[0,0,0]
	v_mfma_scale_f32_16x16x128_f8f6f4 v[12:15], v[152:159], v[176:183], v[240:243], v143, v143 op_sel_hi:[0,0,0]
	v_mfma_scale_f32_16x16x128_f8f6f4 v[4:7], v[144:151], v[184:191], v[244:247], v143, v143 op_sel_hi:[0,0,0]
	v_mfma_scale_f32_16x16x128_f8f6f4 v[0:3], v[152:159], v[184:191], v[248:251], v143, v143 op_sel_hi:[0,0,0]
	s_setprio 0
	s_barrier
	s_add_i32 s53, s53, 2
	s_add_u32 s19, s19, 0x80000
	s_addc_u32 s52, s52, 0
	s_add_u32 s28, s28, 0x100
	s_addc_u32 s29, s29, 0
	s_sub_u32 s19, s19, s101
	s_subb_u32 s52, s52, 0
	s_sub_u32 s28, s28, s98
	s_subb_u32 s29, s29, 0
	s_add_i32 s99, s99, 2
	s_and_b32 s99, s99, 15
	s_cmp_gt_u32 s53, 13
	s_cbranch_scc0 .LBB0_2964
	s_and_b64 vcc, exec, s[14:15]
	s_cbranch_vccz .LBB0_2967
	s_barrier
